# attention restructured: 256-query items, each wave owns two 32-query groups sharing every staged K/V tile and every K/V LDS fragment (P packed in place, one shared reference-max block); compiler-live
# speedup vs baseline: 1.2697x; 1.0379x over previous
; DI int get_tid() { int t = threadIdx.x; asm volatile("" : "+v"(t)); return t; }
; template <int DQK>
; DI void attn_item(const bf16_t* __restrict__ Q, const bf16_t* __restrict__ Kp, const bf16_t* __restrict__ Vt, int q0, int nkeys,
;                   bf16_t* __restrict__ mix, int colbase, int b, char* smem) {
;     ...
;   const int tid = get_tid(), lane = tid & 63, wave = tid >> 6, r = lane & 31, h = lane >> 5;
;   bf16x8 qf[NSTEP];
;   {
;     const bf16_t* qr = Q + (size_t)(q0 + wave * 32 + r) * DQK + 8 * h;
; #pragma unroll
;     for (int s = 0; s < NSTEP; ++s) qf[s] = *(const bf16x8*)(qr + 16 * s);
;   }
;   const int kid0 = tid, kid1 = tid + 256, kid2 = tid + 512;
;   const int kgo0 = (kid0 / KCH) * DQK + (kid0 % KCH) * 8, kgo1 = (kid1 / KCH) * DQK + (kid1 % KCH) * 8, kgo2 = (kid2 / KCH) * DQK + (kid2 % KCH) * 8;
;   const int kso0 = (kid0 / KCH) * KROW + (kid0 % KCH) * 8, kso1 = (kid1 / KCH) * KROW + (kid1 % KCH) * 8, kso2 = (kid2 / KCH) * KROW + (kid2 % KCH) * 8;
;   const int vrow0 = tid >> 3, vcc = (tid & 7) * 8;
;   const bf16_t* Vg0 = Vt + (size_t)vrow0 * NKEY + vcc;
;   const bf16_t* Vg1 = Vt + (size_t)(vrow0 + 32) * NKEY + vcc;
;   const int vso0 = vrow0 * VROW + vcc, vso1 = (vrow0 + 32) * VROW + vcc;
;   uint4 pk0, pk1, pk2, pv0, pv1, qk0, qk1, qk2, qv0, qv1;
;   pk2 = make_uint4(0, 0, 0, 0); qk2 = pk2;
; DI void phase_attn(const Params& p, int layer, char* smem) {
;   const int n_lat = 96 * 32, n_ctx = (layer == 0) ? 96 * 2 : 0;
;   for (int it = blockIdx.x; it < n_lat + n_ctx; it += gridDim.x) {
;     int combo, qb;
;     if (it < n_lat) { int xc = it & 7, j = it >> 3; combo = (j >> 5) * 8 + xc; qb = 2 + (j & 31); }
;     else { int r = it - n_lat; combo = r >> 1; qb = r & 1; }
;     const int type = combo / 48, bh = combo % 48;
;     attn_dispatch(p, type, bh / 6, bh % 6, qb, smem);
.Lat_entry:
	v_writelane_b32 v254, s52, 0
	v_writelane_b32 v254, s53, 1
	v_writelane_b32 v254, s54, 2
	v_writelane_b32 v254, s55, 3
	v_writelane_b32 v254, s56, 4
	v_writelane_b32 v254, s57, 5
	v_writelane_b32 v254, s58, 6
	v_writelane_b32 v254, s59, 7
	v_writelane_b32 v254, s60, 8
	v_writelane_b32 v254, s61, 9
	v_writelane_b32 v254, s62, 10
	v_writelane_b32 v254, s63, 11
	v_writelane_b32 v254, s64, 12
	v_writelane_b32 v254, s65, 13
	v_writelane_b32 v254, s66, 14
	v_writelane_b32 v254, s67, 15
	v_writelane_b32 v254, s68, 16
	v_writelane_b32 v254, s69, 17
	v_writelane_b32 v254, s70, 18
	v_writelane_b32 v254, s71, 19
	v_writelane_b32 v254, s72, 20
	v_writelane_b32 v254, s73, 21
	v_writelane_b32 v254, s74, 22
	v_writelane_b32 v254, s75, 23
	v_writelane_b32 v254, s76, 24
	v_writelane_b32 v254, s77, 25
	v_writelane_b32 v254, s78, 26
	v_writelane_b32 v254, s79, 27
	v_writelane_b32 v254, s80, 28
	v_writelane_b32 v254, s81, 29
	v_writelane_b32 v254, s82, 30
	v_writelane_b32 v254, s83, 31
	v_writelane_b32 v254, s84, 32
	v_writelane_b32 v254, s85, 33
	v_writelane_b32 v254, s86, 34
	v_writelane_b32 v254, s87, 35
	v_writelane_b32 v254, s88, 36
	v_writelane_b32 v254, s89, 37
	v_writelane_b32 v254, s90, 38
	v_writelane_b32 v254, s91, 39
	v_lshlrev_b32_e32 v248, 2, v143
	v_add_u32_e32 v248, 0xac00, v248
	ds_write_b32 v248, v136 offset:0
	ds_write_b32 v248, v137 offset:1024
	ds_write_b32 v248, v138 offset:2048
	ds_write_b32 v248, v139 offset:3072
	ds_write_b32 v248, v141 offset:4096
	ds_write_b32 v248, v142 offset:5120
	ds_write_b32 v248, v188 offset:6144
	ds_write_b32 v248, v189 offset:7168
	ds_write_b32 v248, v190 offset:8192
	ds_write_b32 v248, v191 offset:9216
	ds_write_b32 v248, v192 offset:10240
	ds_write_b32 v248, v193 offset:11264
	ds_write_b32 v248, v194 offset:12288
	ds_write_b32 v248, v195 offset:13312
	ds_write_b32 v248, v196 offset:14336
	ds_write_b32 v248, v197 offset:15360
	ds_write_b32 v248, v198 offset:16384
	ds_write_b32 v248, v199 offset:17408
	ds_write_b32 v248, v200 offset:18432
	ds_write_b32 v248, v201 offset:19456
	ds_write_b32 v248, v202 offset:20480
	ds_write_b32 v248, v203 offset:21504
	ds_write_b32 v248, v204 offset:22528
	ds_write_b32 v248, v205 offset:23552
	ds_write_b32 v248, v206 offset:24576
	ds_write_b32 v248, v207 offset:25600
	ds_write_b32 v248, v208 offset:26624
	ds_write_b32 v248, v209 offset:27648
	ds_write_b32 v248, v210 offset:28672
	ds_write_b32 v248, v211 offset:29696
	ds_write_b32 v248, v212 offset:30720
	ds_write_b32 v248, v234 offset:31744
	ds_write_b32 v248, v235 offset:32768
	ds_write_b32 v248, v236 offset:33792
	v_readlane_b32 s52, v255, 0
	v_lshrrev_b32_e32 v249, 6, v143
	s_nop 0
	v_readfirstlane_b32 s57, v249
	s_mov_b32 s72, s24
	s_mov_b32 s73, s25
	s_add_u32 s76, s24, 0x2000
	s_addc_u32 s77, s25, 0
	s_waitcnt lgkmcnt(0)
.Lat2_item:
	s_cmp_lt_u32 s52, 0x600
	s_cbranch_scc0 .Lat2_done
	s_and_b32 s0, s52, 7
	s_lshr_b32 s1, s52, 3
	s_lshr_b32 s10, s1, 4
	s_lshl_b32 s10, s10, 3
	s_add_u32 s10, s10, s0
	s_and_b32 s1, s1, 15
	s_add_u32 s1, s1, 1
	s_lshl_b32 s56, s1, 8
	s_mov_b32 s53, 0
	s_cmp_ge_u32 s10, 48
	s_cbranch_scc0 .Lat2_ty_1
	s_mov_b32 s53, 1
	s_sub_u32 s10, s10, 48
.Lat2_ty_1:
	s_mul_i32 s54, s10, 43
	s_lshr_b32 s54, s54, 8
	s_mul_i32 s11, s54, 6
	s_sub_u32 s55, s10, s11
	s_cmp_eq_u32 s53, 1
	s_cbranch_scc1 .Lat2_mla_2
	v_and_b32_e32 v248, 31, v143
	v_bfe_u32 v249, v143, 5, 1
	s_lshl_b32 s11, s54, 12
	s_add_u32 s11, s11, s56
	s_sub_u32 s11, s11, 256
	s_lshl_b32 s28, s57, 5
	s_add_u32 s11, s11, s28
	v_add_u32_e32 v141, s11, v248
	v_lshlrev_b32_e32 v141, 6, v141
	v_lshl_add_u32 v141, v249, 3, v141
	s_lshl_b32 s28, s55, 1
	s_add_u32 s28, s28, 8
	s_mul_i32 s28, s28, 0x220000
	v_add_u32_e32 v141, s28, v141
	v_add_u32_e32 v142, 0x220000, v141
	s_mul_i32 s11, s54, 6
	s_add_u32 s11, s11, s55
	s_mul_i32 s28, s11, 0x88000
	s_add_u32 s28, s28, 0x7f80000
	s_add_u32 s58, s24, s28
	s_addc_u32 s59, s25, 0
	s_add_u32 s78, s58, 0x4000
	s_addc_u32 s79, s59, 0
	s_mul_i32 s29, s55, 43
	s_lshr_b32 s29, s29, 7
	s_lshl_b32 s11, s54, 1
	s_add_u32 s11, s11, s29
	s_mul_i32 s28, s11, 0x88000
	s_add_u32 s28, s28, 0x9900000
	s_add_u32 s60, s24, s28
	s_addc_u32 s61, s25, 0
	s_mul_i32 s28, s11, 0x88000
	s_add_u32 s28, s28, 0xa180000
	s_add_u32 s62, s24, s28
	s_addc_u32 s63, s25, 0
	s_lshl_b32 s28, s57, 5
	s_add_u32 s28, s28, s56
	v_add_u32_e32 v253, s28, v248
	s_movk_i32 s29, 128
	v_mul_lo_u32 v253, v253, s29
	v_lshl_add_u32 v253, v249, 4, v253
	s_movk_i32 s29, 144
	v_mul_lo_u32 v128, v248, s29
	v_lshl_add_u32 v128, v249, 4, v128
	s_movk_i32 s29, 136
	v_mul_lo_u32 v129, v248, s29
	v_lshl_add_u32 v129, v249, 3, v129
	v_add_u32_e32 v130, 0x1100, v129
	v_mov_b32_e32 v250, v143
	v_lshrrev_b32_e32 v251, 3, v250
	v_and_b32_e32 v252, 7, v250
	s_movk_i32 s29, 128
	v_mul_lo_u32 v136, v251, s29
	v_lshl_add_u32 v136, v252, 4, v136
	s_movk_i32 s29, 144
	v_mul_lo_u32 v131, v251, s29
	v_lshl_add_u32 v131, v252, 4, v131
	v_add_u32_e32 v250, 256, v143
	v_lshrrev_b32_e32 v251, 3, v250
	v_and_b32_e32 v252, 7, v250
	s_movk_i32 s29, 128
	v_mul_lo_u32 v137, v251, s29
	v_lshl_add_u32 v137, v252, 4, v137
	s_movk_i32 s29, 144
	v_mul_lo_u32 v132, v251, s29
	v_lshl_add_u32 v132, v252, 4, v132
	v_lshrrev_b32_e32 v251, 3, v143
	v_and_b32_e32 v252, 7, v143
	s_movk_i32 s29, 8704
	v_mul_lo_u32 v139, v251, s29
	v_lshl_add_u32 v139, v252, 4, v139
	v_add_u32_e32 v140, 0x44000, v139
	s_movk_i32 s29, 136
	v_mul_lo_u32 v134, v251, s29
	v_lshl_add_u32 v134, v252, 4, v134
	v_add_u32_e32 v135, 0x1100, v134
	s_barrier
; template <int DQK>
; DI void attn_item(const bf16_t* __restrict__ Q, const bf16_t* __restrict__ Kp, const bf16_t* __restrict__ Vt, int q0, int nkeys,
;                   bf16_t* __restrict__ mix, int colbase, int b, char* smem) {
;     ...
;   bf16x8 qf[NSTEP];
;   {
;     const bf16_t* qr = Q + (size_t)(q0 + wave * 32 + r) * DQK + 8 * h;
; #pragma unroll
;     for (int s = 0; s < NSTEP; ++s) qf[s] = *(const bf16x8*)(qr + 16 * s);
;   }
;   const int kid0 = tid, kid1 = tid + 256, kid2 = tid + 512;
;   const int kgo0 = (kid0 / KCH) * DQK + (kid0 % KCH) * 8, kgo1 = (kid1 / KCH) * DQK + (kid1 % KCH) * 8, kgo2 = (kid2 / KCH) * DQK + (kid2 % KCH) * 8;
;   const int kso0 = (kid0 / KCH) * KROW + (kid0 % KCH) * 8, kso1 = (kid1 / KCH) * KROW + (kid1 % KCH) * 8, kso2 = (kid2 / KCH) * KROW + (kid2 % KCH) * 8;
;   const int vrow0 = tid >> 3, vcc = (tid & 7) * 8;
;   const bf16_t* Vg0 = Vt + (size_t)vrow0 * NKEY + vcc;
;   const bf16_t* Vg1 = Vt + (size_t)(vrow0 + 32) * NKEY + vcc;
;   const int vso0 = vrow0 * VROW + vcc, vso1 = (vrow0 + 32) * VROW + vcc;
;   uint4 pk0, pk1, pk2, pv0, pv1, qk0, qk1, qk2, qv0, qv1;
;   pk2 = make_uint4(0, 0, 0, 0); qk2 = pk2;
;     ...
;   f32x16 o0, o1;
; #pragma unroll
;   for (int i = 0; i < 16; ++i) { o0[i] = 0.f; o1[i] = 0.f; }
;     ...
;   const int nt = nkeys >> 6;
;   A_LOAD(p, 0)
;   A_LOAD(q, 64)
;   A_WRITE(p, 0)
;   __syncthreads();
;   if (nt > 2) A_LOAD(p, 128)
	global_load_dwordx4 v[144:147], v253, s[58:59] offset:0
	global_load_dwordx4 v[148:151], v253, s[58:59] offset:32
	global_load_dwordx4 v[152:155], v253, s[58:59] offset:64
	global_load_dwordx4 v[156:159], v253, s[58:59] offset:96
	global_load_dwordx4 v[168:171], v253, s[78:79] offset:0
	global_load_dwordx4 v[172:175], v253, s[78:79] offset:32
	global_load_dwordx4 v[176:179], v253, s[78:79] offset:64
	global_load_dwordx4 v[180:183], v253, s[78:79] offset:96
	s_mov_b32 s1, 0
	s_min_u32 s0, s1, 67
	s_mul_i32 s10, s0, 0x2000
	s_add_u32 s64, s60, s10
	s_addc_u32 s65, s61, 0
	s_lshl_b32 s0, s0, 7
	s_add_u32 s66, s62, s0
	s_addc_u32 s67, s63, 0
	global_load_dwordx4 v[224:227], v136, s[64:65]
	global_load_dwordx4 v[228:231], v137, s[64:65]
	global_load_dwordx4 v[236:239], v139, s[66:67]
	global_load_dwordx4 v[240:243], v140, s[66:67]
	s_waitcnt vmcnt(0)
	ds_write_b128 v131, v[224:227] offset:0
	ds_write_b128 v132, v[228:231] offset:0
	ds_write_b64 v134, v[236:237] offset:18432
	ds_write_b64 v134, v[238:239] offset:18440
	ds_write_b64 v135, v[240:241] offset:18432
	ds_write_b64 v135, v[242:243] offset:18440
	s_mov_b32 s1, 1
	s_min_u32 s0, s1, 67
	s_mul_i32 s10, s0, 0x2000
	s_add_u32 s64, s60, s10
	s_addc_u32 s65, s61, 0
	s_lshl_b32 s0, s0, 7
	s_add_u32 s66, s62, s0
	s_addc_u32 s67, s63, 0
	global_load_dwordx4 v[224:227], v136, s[64:65]
	global_load_dwordx4 v[228:231], v137, s[64:65]
	global_load_dwordx4 v[236:239], v139, s[66:67]
	global_load_dwordx4 v[240:243], v140, s[66:67]
	v_mov_b32_e32 v0, 0
	v_mov_b32_e32 v32, 0
	v_mov_b32_e32 v1, 0
	v_mov_b32_e32 v33, 0
	v_mov_b32_e32 v2, 0
	v_mov_b32_e32 v34, 0
	v_mov_b32_e32 v3, 0
	v_mov_b32_e32 v35, 0
	v_mov_b32_e32 v4, 0
	v_mov_b32_e32 v36, 0
	v_mov_b32_e32 v5, 0
	v_mov_b32_e32 v37, 0
	v_mov_b32_e32 v6, 0
	v_mov_b32_e32 v38, 0
	v_mov_b32_e32 v7, 0
	v_mov_b32_e32 v39, 0
	v_mov_b32_e32 v8, 0
	v_mov_b32_e32 v40, 0
	v_mov_b32_e32 v9, 0
	v_mov_b32_e32 v41, 0
	v_mov_b32_e32 v10, 0
	v_mov_b32_e32 v42, 0
	v_mov_b32_e32 v11, 0
	v_mov_b32_e32 v43, 0
	v_mov_b32_e32 v12, 0
	v_mov_b32_e32 v44, 0
	v_mov_b32_e32 v13, 0
	v_mov_b32_e32 v45, 0
	v_mov_b32_e32 v14, 0
	v_mov_b32_e32 v46, 0
	v_mov_b32_e32 v15, 0
	v_mov_b32_e32 v47, 0
	v_mov_b32_e32 v16, 0
	v_mov_b32_e32 v48, 0
	v_mov_b32_e32 v17, 0
	v_mov_b32_e32 v49, 0
	v_mov_b32_e32 v18, 0
	v_mov_b32_e32 v50, 0
	v_mov_b32_e32 v19, 0
	v_mov_b32_e32 v51, 0
	v_mov_b32_e32 v20, 0
	v_mov_b32_e32 v52, 0
	v_mov_b32_e32 v21, 0
	v_mov_b32_e32 v53, 0
	v_mov_b32_e32 v22, 0
	v_mov_b32_e32 v54, 0
	v_mov_b32_e32 v23, 0
	v_mov_b32_e32 v55, 0
	v_mov_b32_e32 v24, 0
	v_mov_b32_e32 v56, 0
	v_mov_b32_e32 v25, 0
	v_mov_b32_e32 v57, 0
	v_mov_b32_e32 v26, 0
	v_mov_b32_e32 v58, 0
	v_mov_b32_e32 v27, 0
	v_mov_b32_e32 v59, 0
	v_mov_b32_e32 v28, 0
	v_mov_b32_e32 v60, 0
	v_mov_b32_e32 v29, 0
	v_mov_b32_e32 v61, 0
	v_mov_b32_e32 v30, 0
	v_mov_b32_e32 v62, 0
	v_mov_b32_e32 v31, 0
	v_mov_b32_e32 v63, 0
	v_mov_b32_e32 v244, 0
	v_mov_b32_e32 v245, 0
	v_mov_b32_e32 v246, 0
	v_mov_b32_e32 v247, 0
	s_waitcnt lgkmcnt(0)
	s_barrier
	ds_read_b128 v[192:195], v128 offset:0
	ds_read_b128 v[196:199], v128 offset:4608
	ds_read_b128 v[200:203], v128 offset:32
	ds_read_b128 v[204:207], v128 offset:4640
	s_waitcnt lgkmcnt(3)
	v_mfma_f32_32x32x16_bf16 v[64:79], v[192:195], v[144:147], 0
	v_mfma_f32_32x32x16_bf16 v[96:111], v[192:195], v[168:171], 0
	ds_read_b128 v[192:195], v128 offset:64
	s_waitcnt lgkmcnt(3)
	v_mfma_f32_32x32x16_bf16 v[80:95], v[196:199], v[144:147], 0
	v_mfma_f32_32x32x16_bf16 v[112:127], v[196:199], v[168:171], 0
	ds_read_b128 v[196:199], v128 offset:4672
	s_waitcnt lgkmcnt(3)
	v_mfma_f32_32x32x16_bf16 v[64:79], v[200:203], v[148:151], v[64:79]
	v_mfma_f32_32x32x16_bf16 v[96:111], v[200:203], v[172:175], v[96:111]
	ds_read_b128 v[200:203], v128 offset:96
	s_waitcnt lgkmcnt(3)
	v_mfma_f32_32x32x16_bf16 v[80:95], v[204:207], v[148:151], v[80:95]
	v_mfma_f32_32x32x16_bf16 v[112:127], v[204:207], v[172:175], v[112:127]
	ds_read_b128 v[204:207], v128 offset:4704
	s_waitcnt lgkmcnt(3)
	v_mfma_f32_32x32x16_bf16 v[64:79], v[192:195], v[152:155], v[64:79]
	v_mfma_f32_32x32x16_bf16 v[96:111], v[192:195], v[176:179], v[96:111]
	s_waitcnt lgkmcnt(2)
	v_mfma_f32_32x32x16_bf16 v[80:95], v[196:199], v[152:155], v[80:95]
	v_mfma_f32_32x32x16_bf16 v[112:127], v[196:199], v[176:179], v[112:127]
	s_waitcnt lgkmcnt(1)
	v_mfma_f32_32x32x16_bf16 v[64:79], v[200:203], v[156:159], v[64:79]
	v_mfma_f32_32x32x16_bf16 v[96:111], v[200:203], v[180:183], v[96:111]
	s_waitcnt lgkmcnt(0)
; template <int DQK>
; DI void attn_item(const bf16_t* __restrict__ Q, const bf16_t* __restrict__ Kp, const bf16_t* __restrict__ Vt, int q0, int nkeys,
;                   bf16_t* __restrict__ mix, int colbase, int b, char* smem) {
;     ...
;   for (int kt = 0; kt < nt; kt += 2) {
;     A_TILE(0)
;     A_WRITE(q, 1)
;     __syncthreads();
;     if (kt + 3 < nt) A_LOAD(q, (kt + 3) << 6)
	v_mfma_f32_32x32x16_bf16 v[80:95], v[204:207], v[156:159], v[80:95]
	v_mfma_f32_32x32x16_bf16 v[112:127], v[204:207], v[180:183], v[112:127]
	s_nop 7
	s_nop 7
	v_max3_f32 v248, v64, v65, v66
	v_max3_f32 v249, v80, v81, v82
	v_max3_f32 v250, v96, v97, v98
	v_max3_f32 v251, v112, v113, v114
	v_max3_f32 v248, v248, v67, v68
	v_max3_f32 v249, v249, v83, v84
	v_max3_f32 v250, v250, v99, v100
	v_max3_f32 v251, v251, v115, v116
	v_max3_f32 v248, v248, v69, v70
	v_max3_f32 v249, v249, v85, v86
	v_max3_f32 v250, v250, v101, v102
	v_max3_f32 v251, v251, v117, v118
	v_max3_f32 v248, v248, v71, v72
	v_max3_f32 v249, v249, v87, v88
	v_max3_f32 v250, v250, v103, v104
	v_max3_f32 v251, v251, v119, v120
	v_max3_f32 v248, v248, v73, v74
	v_max3_f32 v249, v249, v89, v90
	v_max3_f32 v250, v250, v105, v106
	v_max3_f32 v251, v251, v121, v122
	v_max3_f32 v248, v248, v75, v76
	v_max3_f32 v249, v249, v91, v92
	v_max3_f32 v250, v250, v107, v108
	v_max3_f32 v251, v251, v123, v124
	v_max3_f32 v248, v248, v77, v78
	v_max3_f32 v249, v249, v93, v94
	v_max3_f32 v250, v250, v109, v110
	v_max3_f32 v251, v251, v125, v126
	v_max_f32_e32 v248, v248, v79
	v_max_f32_e32 v249, v249, v95
	v_max_f32_e32 v250, v250, v111
	v_max_f32_e32 v251, v251, v127
	v_max3_f32 v253, v248, v249, v250
	v_max_f32_e32 v253, v253, v251
	v_mov_b32_e32 v252, v253
	s_nop 1
	v_permlane32_swap_b32_e32 v253, v252
	v_max_f32_e32 v253, v253, v252
	v_sub_f32_e32 v64, v64, v253
	v_sub_f32_e32 v65, v65, v253
	v_sub_f32_e32 v66, v66, v253
	v_sub_f32_e32 v67, v67, v253
	v_sub_f32_e32 v68, v68, v253
	v_sub_f32_e32 v69, v69, v253
	v_sub_f32_e32 v70, v70, v253
	v_sub_f32_e32 v71, v71, v253
	v_sub_f32_e32 v72, v72, v253
	v_sub_f32_e32 v73, v73, v253
	v_sub_f32_e32 v74, v74, v253
	v_sub_f32_e32 v75, v75, v253
	v_sub_f32_e32 v76, v76, v253
	v_sub_f32_e32 v77, v77, v253
	v_sub_f32_e32 v78, v78, v253
	v_sub_f32_e32 v79, v79, v253
	v_sub_f32_e32 v80, v80, v253
	v_sub_f32_e32 v81, v81, v253
	v_sub_f32_e32 v82, v82, v253
	v_sub_f32_e32 v83, v83, v253
	v_sub_f32_e32 v84, v84, v253
	v_sub_f32_e32 v85, v85, v253
	v_sub_f32_e32 v86, v86, v253
	v_sub_f32_e32 v87, v87, v253
	v_sub_f32_e32 v88, v88, v253
	v_sub_f32_e32 v89, v89, v253
	v_sub_f32_e32 v90, v90, v253
	v_sub_f32_e32 v91, v91, v253
	v_sub_f32_e32 v92, v92, v253
	v_sub_f32_e32 v93, v93, v253
	v_sub_f32_e32 v94, v94, v253
	v_sub_f32_e32 v95, v95, v253
	v_sub_f32_e32 v96, v96, v253
	v_sub_f32_e32 v97, v97, v253
	v_sub_f32_e32 v98, v98, v253
	v_sub_f32_e32 v99, v99, v253
	v_sub_f32_e32 v100, v100, v253
	v_sub_f32_e32 v101, v101, v253
	v_sub_f32_e32 v102, v102, v253
	v_sub_f32_e32 v103, v103, v253
	v_sub_f32_e32 v104, v104, v253
	v_sub_f32_e32 v105, v105, v253
	v_sub_f32_e32 v106, v106, v253
	v_sub_f32_e32 v107, v107, v253
	v_sub_f32_e32 v108, v108, v253
	v_sub_f32_e32 v109, v109, v253
	v_sub_f32_e32 v110, v110, v253
	v_sub_f32_e32 v111, v111, v253
	v_sub_f32_e32 v112, v112, v253
	v_sub_f32_e32 v113, v113, v253
	v_sub_f32_e32 v114, v114, v253
	v_sub_f32_e32 v115, v115, v253
	v_sub_f32_e32 v116, v116, v253
	v_sub_f32_e32 v117, v117, v253
	v_sub_f32_e32 v118, v118, v253
	v_sub_f32_e32 v119, v119, v253
	v_sub_f32_e32 v120, v120, v253
	v_sub_f32_e32 v121, v121, v253
	v_sub_f32_e32 v122, v122, v253
	v_sub_f32_e32 v123, v123, v253
	v_sub_f32_e32 v124, v124, v253
	v_sub_f32_e32 v125, v125, v253
	v_sub_f32_e32 v126, v126, v253
	v_sub_f32_e32 v127, v127, v253
	v_sub_f32_e32 v208, 0, v253
	v_sub_f32_e32 v209, 0, v253
	v_sub_f32_e32 v210, 0, v253
	v_sub_f32_e32 v211, 0, v253
	v_sub_f32_e32 v212, 0, v253
	v_sub_f32_e32 v213, 0, v253
	v_sub_f32_e32 v214, 0, v253
	v_sub_f32_e32 v215, 0, v253
	v_sub_f32_e32 v216, 0, v253
	v_sub_f32_e32 v217, 0, v253
	v_sub_f32_e32 v218, 0, v253
	v_sub_f32_e32 v219, 0, v253
	v_sub_f32_e32 v220, 0, v253
	v_sub_f32_e32 v221, 0, v253
	v_sub_f32_e32 v222, 0, v253
	v_sub_f32_e32 v223, 0, v253
	s_mov_b32 s68, 0
.Lat2_loop_g:
	s_waitcnt vmcnt(0)
	ds_write_b128 v131, v[224:227] offset:9216
	ds_write_b128 v132, v[228:231] offset:9216
	ds_write_b64 v134, v[236:237] offset:27136
	ds_write_b64 v134, v[238:239] offset:27144
	ds_write_b64 v135, v[240:241] offset:27136
	ds_write_b64 v135, v[242:243] offset:27144
	s_add_u32 s1, s68, 2
	s_min_u32 s0, s1, 67
	s_mul_i32 s10, s0, 0x2000
	s_add_u32 s64, s60, s10
	s_addc_u32 s65, s61, 0
	s_lshl_b32 s0, s0, 7
	s_add_u32 s66, s62, s0
	s_addc_u32 s67, s63, 0
	global_load_dwordx4 v[224:227], v136, s[64:65]
	global_load_dwordx4 v[228:231], v137, s[64:65]
	global_load_dwordx4 v[236:239], v139, s[66:67]
	global_load_dwordx4 v[240:243], v140, s[66:67]
	v_add_u32_e32 v248, 0x4800, v129
	v_add_u32_e32 v249, 0x4800, v130
	ds_read2_b64 v[192:195], v248 offset0:0 offset1:2
	ds_read2_b64 v[196:199], v249 offset0:0 offset1:2
	ds_read2_b64 v[200:203], v248 offset0:4 offset1:6
	ds_read2_b64 v[204:207], v249 offset0:4 offset1:6
	v_exp_f32_e32 v64, v64
	v_exp_f32_e32 v65, v65
	v_exp_f32_e32 v66, v66
	v_exp_f32_e32 v67, v67
	v_exp_f32_e32 v68, v68
	v_exp_f32_e32 v69, v69
	v_exp_f32_e32 v70, v70
	v_exp_f32_e32 v71, v71
	v_exp_f32_e32 v96, v96
	v_exp_f32_e32 v97, v97
	v_exp_f32_e32 v98, v98
	v_exp_f32_e32 v99, v99
	v_exp_f32_e32 v100, v100
	v_exp_f32_e32 v101, v101
	v_exp_f32_e32 v102, v102
	v_exp_f32_e32 v103, v103
	v_add_f32_e32 v244, v244, v64
	v_add_f32_e32 v245, v245, v65
	v_add_f32_e32 v244, v244, v66
	v_add_f32_e32 v245, v245, v67
	v_add_f32_e32 v244, v244, v68
	v_add_f32_e32 v245, v245, v69
	v_add_f32_e32 v244, v244, v70
	v_add_f32_e32 v245, v245, v71
	v_add_f32_e32 v246, v246, v96
	v_add_f32_e32 v247, v247, v97
	v_add_f32_e32 v246, v246, v98
	v_add_f32_e32 v247, v247, v99
	v_add_f32_e32 v246, v246, v100
	v_add_f32_e32 v247, v247, v101
	v_add_f32_e32 v246, v246, v102
	v_add_f32_e32 v247, v247, v103
	v_cvt_pk_bf16_f32 v64, v64, v65
	v_cvt_pk_bf16_f32 v65, v66, v67
	v_cvt_pk_bf16_f32 v66, v68, v69
	v_cvt_pk_bf16_f32 v67, v70, v71
	v_cvt_pk_bf16_f32 v96, v96, v97
	v_cvt_pk_bf16_f32 v97, v98, v99
	v_cvt_pk_bf16_f32 v98, v100, v101
	v_cvt_pk_bf16_f32 v99, v102, v103
	s_waitcnt lgkmcnt(3)
	v_mfma_f32_32x32x16_bf16 v[0:15], v[192:195], v[64:67], v[0:15]
	v_mfma_f32_32x32x16_bf16 v[32:47], v[192:195], v[96:99], v[32:47]
	ds_read2_b64 v[192:195], v248 offset0:8 offset1:10
	s_waitcnt lgkmcnt(3)
	v_mfma_f32_32x32x16_bf16 v[16:31], v[196:199], v[64:67], v[16:31]
	v_mfma_f32_32x32x16_bf16 v[48:63], v[196:199], v[96:99], v[48:63]
	ds_read2_b64 v[196:199], v249 offset0:8 offset1:10
	v_exp_f32_e32 v72, v72
	v_exp_f32_e32 v73, v73
	v_exp_f32_e32 v74, v74
	v_exp_f32_e32 v75, v75
	v_exp_f32_e32 v76, v76
	v_exp_f32_e32 v77, v77
	v_exp_f32_e32 v78, v78
	v_exp_f32_e32 v79, v79
	v_exp_f32_e32 v104, v104
	v_exp_f32_e32 v105, v105
	v_exp_f32_e32 v106, v106
	v_exp_f32_e32 v107, v107
	v_exp_f32_e32 v108, v108
	v_exp_f32_e32 v109, v109
	v_exp_f32_e32 v110, v110
	v_exp_f32_e32 v111, v111
	v_add_f32_e32 v244, v244, v72
	v_add_f32_e32 v245, v245, v73
	v_add_f32_e32 v244, v244, v74
	v_add_f32_e32 v245, v245, v75
	v_add_f32_e32 v244, v244, v76
	v_add_f32_e32 v245, v245, v77
	v_add_f32_e32 v244, v244, v78
	v_add_f32_e32 v245, v245, v79
	v_add_f32_e32 v246, v246, v104
	v_add_f32_e32 v247, v247, v105
	v_add_f32_e32 v246, v246, v106
	v_add_f32_e32 v247, v247, v107
	v_add_f32_e32 v246, v246, v108
	v_add_f32_e32 v247, v247, v109
	v_add_f32_e32 v246, v246, v110
	v_add_f32_e32 v247, v247, v111
	v_cvt_pk_bf16_f32 v68, v72, v73
	v_cvt_pk_bf16_f32 v69, v74, v75
	v_cvt_pk_bf16_f32 v70, v76, v77
	v_cvt_pk_bf16_f32 v71, v78, v79
	v_cvt_pk_bf16_f32 v100, v104, v105
	v_cvt_pk_bf16_f32 v101, v106, v107
	v_cvt_pk_bf16_f32 v102, v108, v109
	v_cvt_pk_bf16_f32 v103, v110, v111
	s_waitcnt lgkmcnt(3)
	v_mfma_f32_32x32x16_bf16 v[0:15], v[200:203], v[68:71], v[0:15]
	v_mfma_f32_32x32x16_bf16 v[32:47], v[200:203], v[100:103], v[32:47]
	ds_read2_b64 v[200:203], v248 offset0:12 offset1:14
	s_waitcnt lgkmcnt(3)
	v_mfma_f32_32x32x16_bf16 v[16:31], v[204:207], v[68:71], v[16:31]
	v_mfma_f32_32x32x16_bf16 v[48:63], v[204:207], v[100:103], v[48:63]
	ds_read2_b64 v[204:207], v249 offset0:12 offset1:14
	v_exp_f32_e32 v80, v80
	v_exp_f32_e32 v81, v81
	v_exp_f32_e32 v82, v82
	v_exp_f32_e32 v83, v83
	v_exp_f32_e32 v84, v84
	v_exp_f32_e32 v85, v85
	v_exp_f32_e32 v86, v86
	v_exp_f32_e32 v87, v87
	v_exp_f32_e32 v112, v112
	v_exp_f32_e32 v113, v113
	v_exp_f32_e32 v114, v114
	v_exp_f32_e32 v115, v115
	v_exp_f32_e32 v116, v116
	v_exp_f32_e32 v117, v117
	v_exp_f32_e32 v118, v118
	v_exp_f32_e32 v119, v119
	v_add_f32_e32 v244, v244, v80
	v_add_f32_e32 v245, v245, v81
	v_add_f32_e32 v244, v244, v82
	v_add_f32_e32 v245, v245, v83
	v_add_f32_e32 v244, v244, v84
	v_add_f32_e32 v245, v245, v85
	v_add_f32_e32 v244, v244, v86
	v_add_f32_e32 v245, v245, v87
	v_add_f32_e32 v246, v246, v112
	v_add_f32_e32 v247, v247, v113
	v_add_f32_e32 v246, v246, v114
	v_add_f32_e32 v247, v247, v115
	v_add_f32_e32 v246, v246, v116
	v_add_f32_e32 v247, v247, v117
	v_add_f32_e32 v246, v246, v118
	v_add_f32_e32 v247, v247, v119
	v_cvt_pk_bf16_f32 v72, v80, v81
	v_cvt_pk_bf16_f32 v73, v82, v83
	v_cvt_pk_bf16_f32 v74, v84, v85
	v_cvt_pk_bf16_f32 v75, v86, v87
	v_cvt_pk_bf16_f32 v104, v112, v113
	v_cvt_pk_bf16_f32 v105, v114, v115
	v_cvt_pk_bf16_f32 v106, v116, v117
	v_cvt_pk_bf16_f32 v107, v118, v119
	s_waitcnt lgkmcnt(3)
	v_mfma_f32_32x32x16_bf16 v[0:15], v[192:195], v[72:75], v[0:15]
	v_mfma_f32_32x32x16_bf16 v[32:47], v[192:195], v[104:107], v[32:47]
	s_waitcnt lgkmcnt(2)
	v_mfma_f32_32x32x16_bf16 v[16:31], v[196:199], v[72:75], v[16:31]
	v_mfma_f32_32x32x16_bf16 v[48:63], v[196:199], v[104:107], v[48:63]
	v_exp_f32_e32 v88, v88
	v_exp_f32_e32 v89, v89
	v_exp_f32_e32 v90, v90
	v_exp_f32_e32 v91, v91
	v_exp_f32_e32 v92, v92
	v_exp_f32_e32 v93, v93
	v_exp_f32_e32 v94, v94
	v_exp_f32_e32 v95, v95
	v_exp_f32_e32 v120, v120
	v_exp_f32_e32 v121, v121
	v_exp_f32_e32 v122, v122
	v_exp_f32_e32 v123, v123
	v_exp_f32_e32 v124, v124
	v_exp_f32_e32 v125, v125
	v_exp_f32_e32 v126, v126
	v_exp_f32_e32 v127, v127
	v_add_f32_e32 v244, v244, v88
	v_add_f32_e32 v245, v245, v89
	v_add_f32_e32 v244, v244, v90
	v_add_f32_e32 v245, v245, v91
	v_add_f32_e32 v244, v244, v92
	v_add_f32_e32 v245, v245, v93
	v_add_f32_e32 v244, v244, v94
	v_add_f32_e32 v245, v245, v95
	v_add_f32_e32 v246, v246, v120
	v_add_f32_e32 v247, v247, v121
	v_add_f32_e32 v246, v246, v122
	v_add_f32_e32 v247, v247, v123
	v_add_f32_e32 v246, v246, v124
	v_add_f32_e32 v247, v247, v125
	v_add_f32_e32 v246, v246, v126
	v_add_f32_e32 v247, v247, v127
	v_cvt_pk_bf16_f32 v76, v88, v89
	v_cvt_pk_bf16_f32 v77, v90, v91
	v_cvt_pk_bf16_f32 v78, v92, v93
	v_cvt_pk_bf16_f32 v79, v94, v95
	v_cvt_pk_bf16_f32 v108, v120, v121
	v_cvt_pk_bf16_f32 v109, v122, v123
	v_cvt_pk_bf16_f32 v110, v124, v125
	v_cvt_pk_bf16_f32 v111, v126, v127
	s_waitcnt lgkmcnt(1)
	v_mfma_f32_32x32x16_bf16 v[0:15], v[200:203], v[76:79], v[0:15]
	v_mfma_f32_32x32x16_bf16 v[32:47], v[200:203], v[108:111], v[32:47]
	s_waitcnt lgkmcnt(0)
	v_mfma_f32_32x32x16_bf16 v[16:31], v[204:207], v[76:79], v[16:31]
	v_mfma_f32_32x32x16_bf16 v[48:63], v[204:207], v[108:111], v[48:63]
	s_add_u32 s68, s68, 1
	s_waitcnt lgkmcnt(0)
	s_barrier
	ds_read_b128 v[192:195], v128 offset:9216
	ds_read_b128 v[196:199], v128 offset:13824
	ds_read_b128 v[200:203], v128 offset:9248
	ds_read_b128 v[204:207], v128 offset:13856
	s_waitcnt lgkmcnt(3)
	v_mfma_f32_32x32x16_bf16 v[64:79], v[192:195], v[144:147], v[208:223]
	v_mfma_f32_32x32x16_bf16 v[96:111], v[192:195], v[168:171], v[208:223]
	ds_read_b128 v[192:195], v128 offset:9280
	s_waitcnt lgkmcnt(3)
	v_mfma_f32_32x32x16_bf16 v[80:95], v[196:199], v[144:147], v[208:223]
	v_mfma_f32_32x32x16_bf16 v[112:127], v[196:199], v[168:171], v[208:223]
	ds_read_b128 v[196:199], v128 offset:13888
	s_waitcnt lgkmcnt(3)
	v_mfma_f32_32x32x16_bf16 v[64:79], v[200:203], v[148:151], v[64:79]
	v_mfma_f32_32x32x16_bf16 v[96:111], v[200:203], v[172:175], v[96:111]
	ds_read_b128 v[200:203], v128 offset:9312
	s_waitcnt lgkmcnt(3)
	v_mfma_f32_32x32x16_bf16 v[80:95], v[204:207], v[148:151], v[80:95]
	v_mfma_f32_32x32x16_bf16 v[112:127], v[204:207], v[172:175], v[112:127]
	ds_read_b128 v[204:207], v128 offset:13920
	s_waitcnt lgkmcnt(3)
	v_mfma_f32_32x32x16_bf16 v[64:79], v[192:195], v[152:155], v[64:79]
	v_mfma_f32_32x32x16_bf16 v[96:111], v[192:195], v[176:179], v[96:111]
	s_waitcnt lgkmcnt(2)
	v_mfma_f32_32x32x16_bf16 v[80:95], v[196:199], v[152:155], v[80:95]
	v_mfma_f32_32x32x16_bf16 v[112:127], v[196:199], v[176:179], v[112:127]
	s_waitcnt lgkmcnt(1)
	v_mfma_f32_32x32x16_bf16 v[64:79], v[200:203], v[156:159], v[64:79]
	v_mfma_f32_32x32x16_bf16 v[96:111], v[200:203], v[180:183], v[96:111]
	s_waitcnt lgkmcnt(0)
	v_mfma_f32_32x32x16_bf16 v[80:95], v[204:207], v[156:159], v[80:95]
	v_mfma_f32_32x32x16_bf16 v[112:127], v[204:207], v[180:183], v[112:127]
	s_waitcnt vmcnt(0)
	ds_write_b128 v131, v[224:227] offset:0
	ds_write_b128 v132, v[228:231] offset:0
	ds_write_b64 v134, v[236:237] offset:18432
	ds_write_b64 v134, v[238:239] offset:18440
	ds_write_b64 v135, v[240:241] offset:18432
	ds_write_b64 v135, v[242:243] offset:18440
	s_add_u32 s1, s68, 2
	s_min_u32 s0, s1, 67
	s_mul_i32 s10, s0, 0x2000
	s_add_u32 s64, s60, s10
	s_addc_u32 s65, s61, 0
	s_lshl_b32 s0, s0, 7
	s_add_u32 s66, s62, s0
	s_addc_u32 s67, s63, 0
	global_load_dwordx4 v[224:227], v136, s[64:65]
	global_load_dwordx4 v[228:231], v137, s[64:65]
	global_load_dwordx4 v[236:239], v139, s[66:67]
	global_load_dwordx4 v[240:243], v140, s[66:67]
	v_add_u32_e32 v248, 0x6a00, v129
	v_add_u32_e32 v249, 0x6a00, v130
	ds_read2_b64 v[192:195], v248 offset0:0 offset1:2
	ds_read2_b64 v[196:199], v249 offset0:0 offset1:2
	ds_read2_b64 v[200:203], v248 offset0:4 offset1:6
	ds_read2_b64 v[204:207], v249 offset0:4 offset1:6
	v_exp_f32_e32 v64, v64
	v_exp_f32_e32 v65, v65
	v_exp_f32_e32 v66, v66
	v_exp_f32_e32 v67, v67
	v_exp_f32_e32 v68, v68
	v_exp_f32_e32 v69, v69
	v_exp_f32_e32 v70, v70
	v_exp_f32_e32 v71, v71
	v_exp_f32_e32 v96, v96
	v_exp_f32_e32 v97, v97
	v_exp_f32_e32 v98, v98
	v_exp_f32_e32 v99, v99
	v_exp_f32_e32 v100, v100
	v_exp_f32_e32 v101, v101
	v_exp_f32_e32 v102, v102
	v_exp_f32_e32 v103, v103
	v_add_f32_e32 v244, v244, v64
	v_add_f32_e32 v245, v245, v65
	v_add_f32_e32 v244, v244, v66
	v_add_f32_e32 v245, v245, v67
	v_add_f32_e32 v244, v244, v68
	v_add_f32_e32 v245, v245, v69
	v_add_f32_e32 v244, v244, v70
	v_add_f32_e32 v245, v245, v71
	v_add_f32_e32 v246, v246, v96
	v_add_f32_e32 v247, v247, v97
	v_add_f32_e32 v246, v246, v98
	v_add_f32_e32 v247, v247, v99
	v_add_f32_e32 v246, v246, v100
	v_add_f32_e32 v247, v247, v101
	v_add_f32_e32 v246, v246, v102
	v_add_f32_e32 v247, v247, v103
	v_cvt_pk_bf16_f32 v64, v64, v65
	v_cvt_pk_bf16_f32 v65, v66, v67
	v_cvt_pk_bf16_f32 v66, v68, v69
	v_cvt_pk_bf16_f32 v67, v70, v71
	v_cvt_pk_bf16_f32 v96, v96, v97
	v_cvt_pk_bf16_f32 v97, v98, v99
	v_cvt_pk_bf16_f32 v98, v100, v101
	v_cvt_pk_bf16_f32 v99, v102, v103
	s_waitcnt lgkmcnt(3)
	v_mfma_f32_32x32x16_bf16 v[0:15], v[192:195], v[64:67], v[0:15]
	v_mfma_f32_32x32x16_bf16 v[32:47], v[192:195], v[96:99], v[32:47]
	ds_read2_b64 v[192:195], v248 offset0:8 offset1:10
	s_waitcnt lgkmcnt(3)
	v_mfma_f32_32x32x16_bf16 v[16:31], v[196:199], v[64:67], v[16:31]
	v_mfma_f32_32x32x16_bf16 v[48:63], v[196:199], v[96:99], v[48:63]
	ds_read2_b64 v[196:199], v249 offset0:8 offset1:10
	v_exp_f32_e32 v72, v72
	v_exp_f32_e32 v73, v73
	v_exp_f32_e32 v74, v74
	v_exp_f32_e32 v75, v75
	v_exp_f32_e32 v76, v76
	v_exp_f32_e32 v77, v77
	v_exp_f32_e32 v78, v78
	v_exp_f32_e32 v79, v79
	v_exp_f32_e32 v104, v104
	v_exp_f32_e32 v105, v105
	v_exp_f32_e32 v106, v106
	v_exp_f32_e32 v107, v107
	v_exp_f32_e32 v108, v108
	v_exp_f32_e32 v109, v109
	v_exp_f32_e32 v110, v110
	v_exp_f32_e32 v111, v111
	v_add_f32_e32 v244, v244, v72
	v_add_f32_e32 v245, v245, v73
	v_add_f32_e32 v244, v244, v74
	v_add_f32_e32 v245, v245, v75
	v_add_f32_e32 v244, v244, v76
	v_add_f32_e32 v245, v245, v77
	v_add_f32_e32 v244, v244, v78
	v_add_f32_e32 v245, v245, v79
	v_add_f32_e32 v246, v246, v104
	v_add_f32_e32 v247, v247, v105
	v_add_f32_e32 v246, v246, v106
	v_add_f32_e32 v247, v247, v107
	v_add_f32_e32 v246, v246, v108
	v_add_f32_e32 v247, v247, v109
	v_add_f32_e32 v246, v246, v110
	v_add_f32_e32 v247, v247, v111
	v_cvt_pk_bf16_f32 v68, v72, v73
	v_cvt_pk_bf16_f32 v69, v74, v75
	v_cvt_pk_bf16_f32 v70, v76, v77
	v_cvt_pk_bf16_f32 v71, v78, v79
	v_cvt_pk_bf16_f32 v100, v104, v105
	v_cvt_pk_bf16_f32 v101, v106, v107
	v_cvt_pk_bf16_f32 v102, v108, v109
	v_cvt_pk_bf16_f32 v103, v110, v111
	s_waitcnt lgkmcnt(3)
	v_mfma_f32_32x32x16_bf16 v[0:15], v[200:203], v[68:71], v[0:15]
	v_mfma_f32_32x32x16_bf16 v[32:47], v[200:203], v[100:103], v[32:47]
	ds_read2_b64 v[200:203], v248 offset0:12 offset1:14
	s_waitcnt lgkmcnt(3)
	v_mfma_f32_32x32x16_bf16 v[16:31], v[204:207], v[68:71], v[16:31]
	v_mfma_f32_32x32x16_bf16 v[48:63], v[204:207], v[100:103], v[48:63]
	ds_read2_b64 v[204:207], v249 offset0:12 offset1:14
	v_exp_f32_e32 v80, v80
	v_exp_f32_e32 v81, v81
	v_exp_f32_e32 v82, v82
	v_exp_f32_e32 v83, v83
	v_exp_f32_e32 v84, v84
	v_exp_f32_e32 v85, v85
	v_exp_f32_e32 v86, v86
	v_exp_f32_e32 v87, v87
	v_exp_f32_e32 v112, v112
	v_exp_f32_e32 v113, v113
	v_exp_f32_e32 v114, v114
	v_exp_f32_e32 v115, v115
	v_exp_f32_e32 v116, v116
	v_exp_f32_e32 v117, v117
	v_exp_f32_e32 v118, v118
	v_exp_f32_e32 v119, v119
	v_add_f32_e32 v244, v244, v80
	v_add_f32_e32 v245, v245, v81
	v_add_f32_e32 v244, v244, v82
	v_add_f32_e32 v245, v245, v83
	v_add_f32_e32 v244, v244, v84
	v_add_f32_e32 v245, v245, v85
	v_add_f32_e32 v244, v244, v86
	v_add_f32_e32 v245, v245, v87
	v_add_f32_e32 v246, v246, v112
	v_add_f32_e32 v247, v247, v113
	v_add_f32_e32 v246, v246, v114
	v_add_f32_e32 v247, v247, v115
	v_add_f32_e32 v246, v246, v116
	v_add_f32_e32 v247, v247, v117
	v_add_f32_e32 v246, v246, v118
	v_add_f32_e32 v247, v247, v119
	v_cvt_pk_bf16_f32 v72, v80, v81
	v_cvt_pk_bf16_f32 v73, v82, v83
	v_cvt_pk_bf16_f32 v74, v84, v85
	v_cvt_pk_bf16_f32 v75, v86, v87
	v_cvt_pk_bf16_f32 v104, v112, v113
	v_cvt_pk_bf16_f32 v105, v114, v115
	v_cvt_pk_bf16_f32 v106, v116, v117
	v_cvt_pk_bf16_f32 v107, v118, v119
	s_waitcnt lgkmcnt(3)
	v_mfma_f32_32x32x16_bf16 v[0:15], v[192:195], v[72:75], v[0:15]
	v_mfma_f32_32x32x16_bf16 v[32:47], v[192:195], v[104:107], v[32:47]
	s_waitcnt lgkmcnt(2)
	v_mfma_f32_32x32x16_bf16 v[16:31], v[196:199], v[72:75], v[16:31]
	v_mfma_f32_32x32x16_bf16 v[48:63], v[196:199], v[104:107], v[48:63]
	v_exp_f32_e32 v88, v88
	v_exp_f32_e32 v89, v89
	v_exp_f32_e32 v90, v90
	v_exp_f32_e32 v91, v91
	v_exp_f32_e32 v92, v92
	v_exp_f32_e32 v93, v93
	v_exp_f32_e32 v94, v94
	v_exp_f32_e32 v95, v95
	v_exp_f32_e32 v120, v120
	v_exp_f32_e32 v121, v121
	v_exp_f32_e32 v122, v122
	v_exp_f32_e32 v123, v123
	v_exp_f32_e32 v124, v124
	v_exp_f32_e32 v125, v125
	v_exp_f32_e32 v126, v126
	v_exp_f32_e32 v127, v127
	v_add_f32_e32 v244, v244, v88
	v_add_f32_e32 v245, v245, v89
	v_add_f32_e32 v244, v244, v90
	v_add_f32_e32 v245, v245, v91
	v_add_f32_e32 v244, v244, v92
	v_add_f32_e32 v245, v245, v93
	v_add_f32_e32 v244, v244, v94
	v_add_f32_e32 v245, v245, v95
	v_add_f32_e32 v246, v246, v120
	v_add_f32_e32 v247, v247, v121
	v_add_f32_e32 v246, v246, v122
	v_add_f32_e32 v247, v247, v123
	v_add_f32_e32 v246, v246, v124
	v_add_f32_e32 v247, v247, v125
	v_add_f32_e32 v246, v246, v126
	v_add_f32_e32 v247, v247, v127
	v_cvt_pk_bf16_f32 v76, v88, v89
	v_cvt_pk_bf16_f32 v77, v90, v91
	v_cvt_pk_bf16_f32 v78, v92, v93
	v_cvt_pk_bf16_f32 v79, v94, v95
	v_cvt_pk_bf16_f32 v108, v120, v121
	v_cvt_pk_bf16_f32 v109, v122, v123
	v_cvt_pk_bf16_f32 v110, v124, v125
	v_cvt_pk_bf16_f32 v111, v126, v127
	s_waitcnt lgkmcnt(1)
	v_mfma_f32_32x32x16_bf16 v[0:15], v[200:203], v[76:79], v[0:15]
	v_mfma_f32_32x32x16_bf16 v[32:47], v[200:203], v[108:111], v[32:47]
	s_waitcnt lgkmcnt(0)
	v_mfma_f32_32x32x16_bf16 v[16:31], v[204:207], v[76:79], v[16:31]
	v_mfma_f32_32x32x16_bf16 v[48:63], v[204:207], v[108:111], v[48:63]
	s_add_u32 s68, s68, 1
	s_waitcnt lgkmcnt(0)
	s_barrier
	ds_read_b128 v[192:195], v128 offset:0
	ds_read_b128 v[196:199], v128 offset:4608
	ds_read_b128 v[200:203], v128 offset:32
	ds_read_b128 v[204:207], v128 offset:4640
	s_waitcnt lgkmcnt(3)
	v_mfma_f32_32x32x16_bf16 v[64:79], v[192:195], v[144:147], v[208:223]
	v_mfma_f32_32x32x16_bf16 v[96:111], v[192:195], v[168:171], v[208:223]
	ds_read_b128 v[192:195], v128 offset:64
	s_waitcnt lgkmcnt(3)
	v_mfma_f32_32x32x16_bf16 v[80:95], v[196:199], v[144:147], v[208:223]
	v_mfma_f32_32x32x16_bf16 v[112:127], v[196:199], v[168:171], v[208:223]
	ds_read_b128 v[196:199], v128 offset:4672
	s_waitcnt lgkmcnt(3)
	v_mfma_f32_32x32x16_bf16 v[64:79], v[200:203], v[148:151], v[64:79]
	v_mfma_f32_32x32x16_bf16 v[96:111], v[200:203], v[172:175], v[96:111]
	ds_read_b128 v[200:203], v128 offset:96
	s_waitcnt lgkmcnt(3)
	v_mfma_f32_32x32x16_bf16 v[80:95], v[204:207], v[148:151], v[80:95]
	v_mfma_f32_32x32x16_bf16 v[112:127], v[204:207], v[172:175], v[112:127]
	ds_read_b128 v[204:207], v128 offset:4704
	s_waitcnt lgkmcnt(3)
	v_mfma_f32_32x32x16_bf16 v[64:79], v[192:195], v[152:155], v[64:79]
	v_mfma_f32_32x32x16_bf16 v[96:111], v[192:195], v[176:179], v[96:111]
	s_waitcnt lgkmcnt(2)
	v_mfma_f32_32x32x16_bf16 v[80:95], v[196:199], v[152:155], v[80:95]
	v_mfma_f32_32x32x16_bf16 v[112:127], v[196:199], v[176:179], v[112:127]
	s_waitcnt lgkmcnt(1)
	v_mfma_f32_32x32x16_bf16 v[64:79], v[200:203], v[156:159], v[64:79]
	v_mfma_f32_32x32x16_bf16 v[96:111], v[200:203], v[180:183], v[96:111]
	s_waitcnt lgkmcnt(0)
	v_mfma_f32_32x32x16_bf16 v[80:95], v[204:207], v[156:159], v[80:95]
	v_mfma_f32_32x32x16_bf16 v[112:127], v[204:207], v[180:183], v[112:127]
	s_cmp_lt_u32 s68, 68
	s_cbranch_scc1 .Lat2_loop_g
; DI unsigned pack2(float lo, float hi) { f32x2_t v = {lo, hi}; bf16x2_t r = __builtin_convertvector(v, bf16x2_t); return __builtin_bit_cast(unsigned, r); }
; DI float xhalf_sum(float x) { auto r = __builtin_amdgcn_permlane32_swap(__float_as_uint(x), __float_as_uint(x), false, false); return __uint_as_float(r[0]) + __uint_as_float(r[1]); }
; template <int DQK>
; DI void attn_item(const bf16_t* __restrict__ Q, const bf16_t* __restrict__ Kp, const bf16_t* __restrict__ Vt, int q0, int nkeys,
;                   bf16_t* __restrict__ mix, int colbase, int b, char* smem) {
;     ...
;   l = xhalf_sum(l);
;   const float inv = 1.0f / l;
;   const int kp = q0 + wave * 32 + r;
;   bf16_t* orow = mix + (size_t)row_of(b, kp) * D + colbase;
; #pragma unroll
;   for (int g = 0; g < 4; ++g) {
;     uint2 w0, w1;
;     w0.x = pack2(o0[4 * g] * inv, o0[4 * g + 1] * inv); w0.y = pack2(o0[4 * g + 2] * inv, o0[4 * g + 3] * inv);
;     w1.x = pack2(o1[4 * g] * inv, o1[4 * g + 1] * inv); w1.y = pack2(o1[4 * g + 2] * inv, o1[4 * g + 3] * inv);
;     *(uint2*)(orow + 8 * g + 4 * h) = w0;
;     *(uint2*)(orow + 32 + 8 * g + 4 * h) = w1;
;   }
	s_waitcnt vmcnt(0)
	s_nop 7
	s_nop 7
	v_add_f32_e32 v244, v244, v245
	v_add_f32_e32 v246, v246, v247
	v_mov_b32_e32 v248, v244
	v_mov_b32_e32 v249, v246
	s_nop 1
	v_permlane32_swap_b32_e32 v244, v248
	v_permlane32_swap_b32_e32 v246, v249
	v_add_f32_e32 v244, v244, v248
	v_add_f32_e32 v246, v246, v249
	v_mov_b32_e32 v248, 0
	v_fmac_f32_e32 v248, 0, v0
	v_fmac_f32_e32 v248, 0, v1
	v_fmac_f32_e32 v248, 0, v2
	v_fmac_f32_e32 v248, 0, v3
	v_fmac_f32_e32 v248, 0, v4
	v_fmac_f32_e32 v248, 0, v5
	v_fmac_f32_e32 v248, 0, v6
	v_fmac_f32_e32 v248, 0, v7
	v_fmac_f32_e32 v248, 0, v8
	v_fmac_f32_e32 v248, 0, v9
	v_fmac_f32_e32 v248, 0, v10
	v_fmac_f32_e32 v248, 0, v11
	v_fmac_f32_e32 v248, 0, v12
	v_fmac_f32_e32 v248, 0, v13
	v_fmac_f32_e32 v248, 0, v14
	v_fmac_f32_e32 v248, 0, v15
	v_fmac_f32_e32 v248, 0, v16
	v_fmac_f32_e32 v248, 0, v17
	v_fmac_f32_e32 v248, 0, v18
	v_fmac_f32_e32 v248, 0, v19
	v_fmac_f32_e32 v248, 0, v20
	v_fmac_f32_e32 v248, 0, v21
	v_fmac_f32_e32 v248, 0, v22
	v_fmac_f32_e32 v248, 0, v23
	v_fmac_f32_e32 v248, 0, v24
	v_fmac_f32_e32 v248, 0, v25
	v_fmac_f32_e32 v248, 0, v26
	v_fmac_f32_e32 v248, 0, v27
	v_fmac_f32_e32 v248, 0, v28
	v_fmac_f32_e32 v248, 0, v29
	v_fmac_f32_e32 v248, 0, v30
	v_fmac_f32_e32 v248, 0, v31
	v_fmac_f32_e32 v248, 0, v32
	v_fmac_f32_e32 v248, 0, v33
	v_fmac_f32_e32 v248, 0, v34
	v_fmac_f32_e32 v248, 0, v35
	v_fmac_f32_e32 v248, 0, v36
	v_fmac_f32_e32 v248, 0, v37
	v_fmac_f32_e32 v248, 0, v38
	v_fmac_f32_e32 v248, 0, v39
	v_fmac_f32_e32 v248, 0, v40
	v_fmac_f32_e32 v248, 0, v41
	v_fmac_f32_e32 v248, 0, v42
	v_fmac_f32_e32 v248, 0, v43
	v_fmac_f32_e32 v248, 0, v44
	v_fmac_f32_e32 v248, 0, v45
	v_fmac_f32_e32 v248, 0, v46
	v_fmac_f32_e32 v248, 0, v47
	v_fmac_f32_e32 v248, 0, v48
	v_fmac_f32_e32 v248, 0, v49
	v_fmac_f32_e32 v248, 0, v50
	v_fmac_f32_e32 v248, 0, v51
	v_fmac_f32_e32 v248, 0, v52
	v_fmac_f32_e32 v248, 0, v53
	v_fmac_f32_e32 v248, 0, v54
	v_fmac_f32_e32 v248, 0, v55
	v_fmac_f32_e32 v248, 0, v56
	v_fmac_f32_e32 v248, 0, v57
	v_fmac_f32_e32 v248, 0, v58
	v_fmac_f32_e32 v248, 0, v59
	v_fmac_f32_e32 v248, 0, v60
	v_fmac_f32_e32 v248, 0, v61
	v_fmac_f32_e32 v248, 0, v62
	v_fmac_f32_e32 v248, 0, v63
	v_mov_b32_e32 v249, 0x71800000
	v_mov_b32_e32 v250, 0x21800000
	v_cmp_neq_f32_e32 vcc, 0, v248
	s_mov_b64 s[44:45], vcc
	v_cmp_nlt_f32_e32 vcc, v244, v249
	s_or_b64 s[44:45], vcc, s[44:45]
	v_cmp_ngt_f32_e32 vcc, v244, v250
	s_or_b64 s[44:45], vcc, s[44:45]
	v_cmp_nlt_f32_e32 vcc, v246, v249
	s_or_b64 s[44:45], vcc, s[44:45]
	v_cmp_ngt_f32_e32 vcc, v246, v250
	s_or_b64 s[44:45], vcc, s[44:45]
	s_cmp_lg_u64 s[44:45], 0
	s_cselect_b32 s0, 1, 0
	v_mov_b32_e32 v250, s0
	s_lshl_b32 s1, s57, 2
	s_add_u32 s1, s1, 0x13400
	v_mov_b32_e32 v251, s1
	v_mov_b32_e32 v252, 0x13400
	ds_write_b32 v251, v250
	s_waitcnt lgkmcnt(0)
	s_barrier
	ds_read_b128 v[192:195], v252
	s_waitcnt lgkmcnt(0)
	v_or3_b32 v250, v192, v193, v194
	v_or_b32_e32 v250, v250, v195
	s_nop 0
	v_readfirstlane_b32 s0, v250
	s_nop 3
	s_cmp_eq_u32 s0, 0
	s_cbranch_scc0 .Lat2_fallback
	v_rcp_f32_e32 v248, v244
	v_rcp_f32_e32 v249, v246
	s_nop 0
	v_mul_f32_e32 v64, v0, v248
	v_mul_f32_e32 v65, v1, v248
	v_mul_f32_e32 v66, v2, v248
	v_mul_f32_e32 v67, v3, v248
	v_cvt_pk_bf16_f32 v192, v64, v65
	v_cvt_pk_bf16_f32 v193, v66, v67
	global_store_dwordx2 v141, v[192:193], s[72:73] offset:0
	v_mul_f32_e32 v64, v16, v248
	v_mul_f32_e32 v65, v17, v248
	v_mul_f32_e32 v66, v18, v248
	v_mul_f32_e32 v67, v19, v248
	v_cvt_pk_bf16_f32 v194, v64, v65
	v_cvt_pk_bf16_f32 v195, v66, v67
	global_store_dwordx2 v142, v[194:195], s[72:73] offset:0
	v_mul_f32_e32 v64, v4, v248
	v_mul_f32_e32 v65, v5, v248
	v_mul_f32_e32 v66, v6, v248
	v_mul_f32_e32 v67, v7, v248
	v_cvt_pk_bf16_f32 v196, v64, v65
	v_cvt_pk_bf16_f32 v197, v66, v67
	global_store_dwordx2 v141, v[196:197], s[72:73] offset:16
	v_mul_f32_e32 v64, v20, v248
	v_mul_f32_e32 v65, v21, v248
	v_mul_f32_e32 v66, v22, v248
	v_mul_f32_e32 v67, v23, v248
	v_cvt_pk_bf16_f32 v198, v64, v65
	v_cvt_pk_bf16_f32 v199, v66, v67
	global_store_dwordx2 v142, v[198:199], s[72:73] offset:16
	v_mul_f32_e32 v64, v8, v248
	v_mul_f32_e32 v65, v9, v248
	v_mul_f32_e32 v66, v10, v248
	v_mul_f32_e32 v67, v11, v248
	v_cvt_pk_bf16_f32 v200, v64, v65
	v_cvt_pk_bf16_f32 v201, v66, v67
	global_store_dwordx2 v141, v[200:201], s[72:73] offset:32
	v_mul_f32_e32 v64, v24, v248
	v_mul_f32_e32 v65, v25, v248
	v_mul_f32_e32 v66, v26, v248
	v_mul_f32_e32 v67, v27, v248
	v_cvt_pk_bf16_f32 v202, v64, v65
	v_cvt_pk_bf16_f32 v203, v66, v67
	global_store_dwordx2 v142, v[202:203], s[72:73] offset:32
	v_mul_f32_e32 v64, v12, v248
	v_mul_f32_e32 v65, v13, v248
	v_mul_f32_e32 v66, v14, v248
	v_mul_f32_e32 v67, v15, v248
	v_cvt_pk_bf16_f32 v204, v64, v65
	v_cvt_pk_bf16_f32 v205, v66, v67
	global_store_dwordx2 v141, v[204:205], s[72:73] offset:48
	v_mul_f32_e32 v64, v28, v248
	v_mul_f32_e32 v65, v29, v248
	v_mul_f32_e32 v66, v30, v248
	v_mul_f32_e32 v67, v31, v248
	v_cvt_pk_bf16_f32 v206, v64, v65
	v_cvt_pk_bf16_f32 v207, v66, v67
	global_store_dwordx2 v142, v[206:207], s[72:73] offset:48
	v_mul_f32_e32 v64, v32, v249
	v_mul_f32_e32 v65, v33, v249
	v_mul_f32_e32 v66, v34, v249
	v_mul_f32_e32 v67, v35, v249
	v_cvt_pk_bf16_f32 v192, v64, v65
	v_cvt_pk_bf16_f32 v193, v66, v67
	global_store_dwordx2 v141, v[192:193], s[76:77] offset:0
	v_mul_f32_e32 v64, v48, v249
	v_mul_f32_e32 v65, v49, v249
	v_mul_f32_e32 v66, v50, v249
	v_mul_f32_e32 v67, v51, v249
	v_cvt_pk_bf16_f32 v194, v64, v65
	v_cvt_pk_bf16_f32 v195, v66, v67
	global_store_dwordx2 v142, v[194:195], s[76:77] offset:0
	v_mul_f32_e32 v64, v36, v249
	v_mul_f32_e32 v65, v37, v249
	v_mul_f32_e32 v66, v38, v249
	v_mul_f32_e32 v67, v39, v249
	v_cvt_pk_bf16_f32 v196, v64, v65
	v_cvt_pk_bf16_f32 v197, v66, v67
	global_store_dwordx2 v141, v[196:197], s[76:77] offset:16
	v_mul_f32_e32 v64, v52, v249
	v_mul_f32_e32 v65, v53, v249
	v_mul_f32_e32 v66, v54, v249
	v_mul_f32_e32 v67, v55, v249
	v_cvt_pk_bf16_f32 v198, v64, v65
	v_cvt_pk_bf16_f32 v199, v66, v67
	global_store_dwordx2 v142, v[198:199], s[76:77] offset:16
	v_mul_f32_e32 v64, v40, v249
	v_mul_f32_e32 v65, v41, v249
	v_mul_f32_e32 v66, v42, v249
	v_mul_f32_e32 v67, v43, v249
	v_cvt_pk_bf16_f32 v200, v64, v65
	v_cvt_pk_bf16_f32 v201, v66, v67
	global_store_dwordx2 v141, v[200:201], s[76:77] offset:32
	v_mul_f32_e32 v64, v56, v249
	v_mul_f32_e32 v65, v57, v249
	v_mul_f32_e32 v66, v58, v249
	v_mul_f32_e32 v67, v59, v249
	v_cvt_pk_bf16_f32 v202, v64, v65
	v_cvt_pk_bf16_f32 v203, v66, v67
	global_store_dwordx2 v142, v[202:203], s[76:77] offset:32
	v_mul_f32_e32 v64, v44, v249
	v_mul_f32_e32 v65, v45, v249
	v_mul_f32_e32 v66, v46, v249
	v_mul_f32_e32 v67, v47, v249
	v_cvt_pk_bf16_f32 v204, v64, v65
	v_cvt_pk_bf16_f32 v205, v66, v67
	global_store_dwordx2 v141, v[204:205], s[76:77] offset:48
	v_mul_f32_e32 v64, v60, v249
	v_mul_f32_e32 v65, v61, v249
	v_mul_f32_e32 v66, v62, v249
	v_mul_f32_e32 v67, v63, v249
	v_cvt_pk_bf16_f32 v206, v64, v65
	v_cvt_pk_bf16_f32 v207, v66, v67
	global_store_dwordx2 v142, v[206:207], s[76:77] offset:48
	s_branch .Lat2_next
; DI int get_tid() { int t = threadIdx.x; asm volatile("" : "+v"(t)); return t; }
; template <int DQK>
; DI void attn_item(const bf16_t* __restrict__ Q, const bf16_t* __restrict__ Kp, const bf16_t* __restrict__ Vt, int q0, int nkeys,
;                   bf16_t* __restrict__ mix, int colbase, int b, char* smem) {
;     ...
;   const int tid = get_tid(), lane = tid & 63, wave = tid >> 6, r = lane & 31, h = lane >> 5;
;   bf16x8 qf[NSTEP];
;   {
;     const bf16_t* qr = Q + (size_t)(q0 + wave * 32 + r) * DQK + 8 * h;
; #pragma unroll
;     for (int s = 0; s < NSTEP; ++s) qf[s] = *(const bf16x8*)(qr + 16 * s);
;   }
;   const int kid0 = tid, kid1 = tid + 256, kid2 = tid + 512;
;   const int kgo0 = (kid0 / KCH) * DQK + (kid0 % KCH) * 8, kgo1 = (kid1 / KCH) * DQK + (kid1 % KCH) * 8, kgo2 = (kid2 / KCH) * DQK + (kid2 % KCH) * 8;
;   const int kso0 = (kid0 / KCH) * KROW + (kid0 % KCH) * 8, kso1 = (kid1 / KCH) * KROW + (kid1 % KCH) * 8, kso2 = (kid2 / KCH) * KROW + (kid2 % KCH) * 8;
;   const int vrow0 = tid >> 3, vcc = (tid & 7) * 8;
;   const bf16_t* Vg0 = Vt + (size_t)vrow0 * NKEY + vcc;
;   const bf16_t* Vg1 = Vt + (size_t)(vrow0 + 32) * NKEY + vcc;
;   const int vso0 = vrow0 * VROW + vcc, vso1 = (vrow0 + 32) * VROW + vcc;
;   uint4 pk0, pk1, pk2, pv0, pv1, qk0, qk1, qk2, qv0, qv1;
;   pk2 = make_uint4(0, 0, 0, 0); qk2 = pk2;
;     ...
;   f32x16 o0, o1;
; #pragma unroll
;   for (int i = 0; i < 16; ++i) { o0[i] = 0.f; o1[i] = 0.f; }
; DI void attn_dispatch(const Params& p, int type, int b, int hd, int qb, char* smem) {
;   bf16_t* MIX = (bf16_t*)(p.ws + OFF_U);
;   const int nkeys = qb < 2 ? CTX : NKEY;
;   if (type == 0) {
;     const bf16_t* Q = (const bf16_t*)(p.ws + OFF_QG) + (size_t)(b * 6 + hd) * NKEY * 64;
;     const bf16_t* K = (const bf16_t*)(p.ws + OFF_KG) + (size_t)(b * 2 + hd / 3) * NKEY * 64;
;     const bf16_t* V = (const bf16_t*)(p.ws + OFF_VGT) + (size_t)(b * 2 + hd / 3) * 64 * NKEY;
;     attn_item<64>(Q, K, V, qb * 128, nkeys, MIX, 256 + hd * 64, b, smem);
;   } else {
;     const bf16_t* Q = (const bf16_t*)(p.ws + OFF_QM) + (size_t)(b * 6 + hd) * NKEY * 96;
;     const bf16_t* K = (const bf16_t*)(p.ws + OFF_KM) + (size_t)(b * 6 + hd) * NKEY * 96;
;     const bf16_t* V = (const bf16_t*)(p.ws + OFF_VMT) + (size_t)(b * 6 + hd) * 64 * NKEY;
;     attn_item<96>(Q, K, V, qb * 128, nkeys, MIX, 640 + hd * 64, b, smem);
;   }
.Lat2_mla_2:
	v_and_b32_e32 v248, 31, v143
	v_bfe_u32 v249, v143, 5, 1
	s_lshl_b32 s11, s54, 12
	s_add_u32 s11, s11, s56
	s_sub_u32 s11, s11, 256
	s_lshl_b32 s28, s57, 5
	s_add_u32 s11, s11, s28
	v_add_u32_e32 v141, s11, v248
	v_lshlrev_b32_e32 v141, 6, v141
	v_lshl_add_u32 v141, v249, 3, v141
	s_lshl_b32 s28, s55, 1
	s_add_u32 s28, s28, 20
	s_mul_i32 s28, s28, 0x220000
	v_add_u32_e32 v141, s28, v141
	v_add_u32_e32 v142, 0x220000, v141
	s_mul_i32 s11, s54, 6
	s_add_u32 s11, s11, s55
	s_mul_i32 s28, s11, 0xcc000
	s_add_u32 s28, s28, 0xaa00000
	s_add_u32 s58, s24, s28
	s_addc_u32 s59, s25, 0
	s_add_u32 s78, s58, 0x6000
	s_addc_u32 s79, s59, 0
	s_mul_i32 s28, s11, 0xcc000
	s_add_u32 s28, s28, 0xd040000
	s_add_u32 s60, s24, s28
	s_addc_u32 s61, s25, 0
	s_mul_i32 s28, s11, 0x88000
	s_add_u32 s28, s28, 0xf680000
	s_add_u32 s62, s24, s28
	s_addc_u32 s63, s25, 0
	s_lshl_b32 s28, s57, 5
	s_add_u32 s28, s28, s56
	v_add_u32_e32 v253, s28, v248
	s_movk_i32 s29, 192
	v_mul_lo_u32 v253, v253, s29
	v_lshl_add_u32 v253, v249, 4, v253
	s_movk_i32 s29, 208
	v_mul_lo_u32 v128, v248, s29
	v_lshl_add_u32 v128, v249, 4, v128
	s_movk_i32 s29, 136
	v_mul_lo_u32 v129, v248, s29
	v_lshl_add_u32 v129, v249, 3, v129
	v_add_u32_e32 v130, 0x1100, v129
	v_mov_b32_e32 v250, v143
	v_mul_u32_u24_e32 v251, 0xaaab, v250
	v_lshrrev_b32_e32 v251, 19, v251
	v_mul_u32_u24_e32 v252, 12, v251
	v_sub_u32_e32 v252, v250, v252
	s_movk_i32 s29, 192
	v_mul_lo_u32 v136, v251, s29
	v_lshl_add_u32 v136, v252, 4, v136
	s_movk_i32 s29, 208
	v_mul_lo_u32 v131, v251, s29
	v_lshl_add_u32 v131, v252, 4, v131
	v_add_u32_e32 v250, 256, v143
	v_mul_u32_u24_e32 v251, 0xaaab, v250
	v_lshrrev_b32_e32 v251, 19, v251
	v_mul_u32_u24_e32 v252, 12, v251
	v_sub_u32_e32 v252, v250, v252
	s_movk_i32 s29, 192
	v_mul_lo_u32 v137, v251, s29
	v_lshl_add_u32 v137, v252, 4, v137
	s_movk_i32 s29, 208
	v_mul_lo_u32 v132, v251, s29
	v_lshl_add_u32 v132, v252, 4, v132
	v_add_u32_e32 v250, 512, v143
	v_mul_u32_u24_e32 v251, 0xaaab, v250
	v_lshrrev_b32_e32 v251, 19, v251
	v_mul_u32_u24_e32 v252, 12, v251
	v_sub_u32_e32 v252, v250, v252
	s_movk_i32 s29, 192
	v_mul_lo_u32 v138, v251, s29
	v_lshl_add_u32 v138, v252, 4, v138
	s_movk_i32 s29, 208
	v_mul_lo_u32 v133, v251, s29
	v_lshl_add_u32 v133, v252, 4, v133
	v_lshrrev_b32_e32 v251, 3, v143
	v_and_b32_e32 v252, 7, v143
	s_movk_i32 s29, 8704
	v_mul_lo_u32 v139, v251, s29
	v_lshl_add_u32 v139, v252, 4, v139
	v_add_u32_e32 v140, 0x44000, v139
	s_movk_i32 s29, 136
	v_mul_lo_u32 v134, v251, s29
	v_lshl_add_u32 v134, v252, 4, v134
	v_add_u32_e32 v135, 0x1100, v134
	s_barrier
	global_load_dwordx4 v[144:147], v253, s[58:59] offset:0
	global_load_dwordx4 v[148:151], v253, s[58:59] offset:32
	global_load_dwordx4 v[152:155], v253, s[58:59] offset:64
	global_load_dwordx4 v[156:159], v253, s[58:59] offset:96
	global_load_dwordx4 v[160:163], v253, s[58:59] offset:128
	global_load_dwordx4 v[164:167], v253, s[58:59] offset:160
	global_load_dwordx4 v[168:171], v253, s[78:79] offset:0
	global_load_dwordx4 v[172:175], v253, s[78:79] offset:32
	global_load_dwordx4 v[176:179], v253, s[78:79] offset:64
	global_load_dwordx4 v[180:183], v253, s[78:79] offset:96
	global_load_dwordx4 v[184:187], v253, s[78:79] offset:128
	global_load_dwordx4 v[188:191], v253, s[78:79] offset:160
	s_mov_b32 s1, 0
	s_min_u32 s0, s1, 67
	s_mul_i32 s10, s0, 0x3000
	s_add_u32 s64, s60, s10
	s_addc_u32 s65, s61, 0
	s_lshl_b32 s0, s0, 7
	s_add_u32 s66, s62, s0
	s_addc_u32 s67, s63, 0
	global_load_dwordx4 v[224:227], v136, s[64:65]
	global_load_dwordx4 v[228:231], v137, s[64:65]
	global_load_dwordx4 v[232:235], v138, s[64:65]
	global_load_dwordx4 v[236:239], v139, s[66:67]
	global_load_dwordx4 v[240:243], v140, s[66:67]
	s_waitcnt vmcnt(0)
	ds_write_b128 v131, v[224:227] offset:0
	ds_write_b128 v132, v[228:231] offset:0
	ds_write_b128 v133, v[232:235] offset:0
	ds_write_b64 v134, v[236:237] offset:26624
	ds_write_b64 v134, v[238:239] offset:26632
	ds_write_b64 v135, v[240:241] offset:26624
	ds_write_b64 v135, v[242:243] offset:26632
	s_mov_b32 s1, 1
	s_min_u32 s0, s1, 67
	s_mul_i32 s10, s0, 0x3000
	s_add_u32 s64, s60, s10
	s_addc_u32 s65, s61, 0
	s_lshl_b32 s0, s0, 7
	s_add_u32 s66, s62, s0
	s_addc_u32 s67, s63, 0
	global_load_dwordx4 v[224:227], v136, s[64:65]
	global_load_dwordx4 v[228:231], v137, s[64:65]
	global_load_dwordx4 v[232:235], v138, s[64:65]
	global_load_dwordx4 v[236:239], v139, s[66:67]
	global_load_dwordx4 v[240:243], v140, s[66:67]
	v_mov_b32_e32 v0, 0
	v_mov_b32_e32 v32, 0
	v_mov_b32_e32 v1, 0
	v_mov_b32_e32 v33, 0
	v_mov_b32_e32 v2, 0
	v_mov_b32_e32 v34, 0
	v_mov_b32_e32 v3, 0
	v_mov_b32_e32 v35, 0
	v_mov_b32_e32 v4, 0
	v_mov_b32_e32 v36, 0
	v_mov_b32_e32 v5, 0
	v_mov_b32_e32 v37, 0
	v_mov_b32_e32 v6, 0
	v_mov_b32_e32 v38, 0
	v_mov_b32_e32 v7, 0
	v_mov_b32_e32 v39, 0
	v_mov_b32_e32 v8, 0
	v_mov_b32_e32 v40, 0
	v_mov_b32_e32 v9, 0
	v_mov_b32_e32 v41, 0
	v_mov_b32_e32 v10, 0
	v_mov_b32_e32 v42, 0
	v_mov_b32_e32 v11, 0
	v_mov_b32_e32 v43, 0
	v_mov_b32_e32 v12, 0
	v_mov_b32_e32 v44, 0
	v_mov_b32_e32 v13, 0
	v_mov_b32_e32 v45, 0
	v_mov_b32_e32 v14, 0
	v_mov_b32_e32 v46, 0
	v_mov_b32_e32 v15, 0
	v_mov_b32_e32 v47, 0
	v_mov_b32_e32 v16, 0
	v_mov_b32_e32 v48, 0
	v_mov_b32_e32 v17, 0
	v_mov_b32_e32 v49, 0
	v_mov_b32_e32 v18, 0
	v_mov_b32_e32 v50, 0
	v_mov_b32_e32 v19, 0
	v_mov_b32_e32 v51, 0
	v_mov_b32_e32 v20, 0
	v_mov_b32_e32 v52, 0
	v_mov_b32_e32 v21, 0
	v_mov_b32_e32 v53, 0
	v_mov_b32_e32 v22, 0
	v_mov_b32_e32 v54, 0
	v_mov_b32_e32 v23, 0
	v_mov_b32_e32 v55, 0
	v_mov_b32_e32 v24, 0
	v_mov_b32_e32 v56, 0
	v_mov_b32_e32 v25, 0
	v_mov_b32_e32 v57, 0
	v_mov_b32_e32 v26, 0
	v_mov_b32_e32 v58, 0
	v_mov_b32_e32 v27, 0
	v_mov_b32_e32 v59, 0
	v_mov_b32_e32 v28, 0
	v_mov_b32_e32 v60, 0
	v_mov_b32_e32 v29, 0
	v_mov_b32_e32 v61, 0
	v_mov_b32_e32 v30, 0
	v_mov_b32_e32 v62, 0
	v_mov_b32_e32 v31, 0
	v_mov_b32_e32 v63, 0
	v_mov_b32_e32 v244, 0
	v_mov_b32_e32 v245, 0
	v_mov_b32_e32 v246, 0
	v_mov_b32_e32 v247, 0
	s_waitcnt lgkmcnt(0)
	s_barrier
	ds_read_b128 v[192:195], v128 offset:0
	ds_read_b128 v[196:199], v128 offset:6656
	ds_read_b128 v[200:203], v128 offset:32
	ds_read_b128 v[204:207], v128 offset:6688
	s_waitcnt lgkmcnt(3)
	v_mfma_f32_32x32x16_bf16 v[64:79], v[192:195], v[144:147], 0
	v_mfma_f32_32x32x16_bf16 v[96:111], v[192:195], v[168:171], 0
	ds_read_b128 v[192:195], v128 offset:64
	s_waitcnt lgkmcnt(3)
	v_mfma_f32_32x32x16_bf16 v[80:95], v[196:199], v[144:147], 0
	v_mfma_f32_32x32x16_bf16 v[112:127], v[196:199], v[168:171], 0
	ds_read_b128 v[196:199], v128 offset:6720
	s_waitcnt lgkmcnt(3)
	v_mfma_f32_32x32x16_bf16 v[64:79], v[200:203], v[148:151], v[64:79]
	v_mfma_f32_32x32x16_bf16 v[96:111], v[200:203], v[172:175], v[96:111]
	ds_read_b128 v[200:203], v128 offset:96
	s_waitcnt lgkmcnt(3)
	v_mfma_f32_32x32x16_bf16 v[80:95], v[204:207], v[148:151], v[80:95]
	v_mfma_f32_32x32x16_bf16 v[112:127], v[204:207], v[172:175], v[112:127]
	ds_read_b128 v[204:207], v128 offset:6752
	s_waitcnt lgkmcnt(3)
	v_mfma_f32_32x32x16_bf16 v[64:79], v[192:195], v[152:155], v[64:79]
	v_mfma_f32_32x32x16_bf16 v[96:111], v[192:195], v[176:179], v[96:111]
	ds_read_b128 v[192:195], v128 offset:128
	s_waitcnt lgkmcnt(3)
	v_mfma_f32_32x32x16_bf16 v[80:95], v[196:199], v[152:155], v[80:95]
	v_mfma_f32_32x32x16_bf16 v[112:127], v[196:199], v[176:179], v[112:127]
	ds_read_b128 v[196:199], v128 offset:6784
	s_waitcnt lgkmcnt(3)
	v_mfma_f32_32x32x16_bf16 v[64:79], v[200:203], v[156:159], v[64:79]
	v_mfma_f32_32x32x16_bf16 v[96:111], v[200:203], v[180:183], v[96:111]
	ds_read_b128 v[200:203], v128 offset:160
	s_waitcnt lgkmcnt(3)
	v_mfma_f32_32x32x16_bf16 v[80:95], v[204:207], v[156:159], v[80:95]
	v_mfma_f32_32x32x16_bf16 v[112:127], v[204:207], v[180:183], v[112:127]
	ds_read_b128 v[204:207], v128 offset:6816
	s_waitcnt lgkmcnt(3)
	v_mfma_f32_32x32x16_bf16 v[64:79], v[192:195], v[160:163], v[64:79]
	v_mfma_f32_32x32x16_bf16 v[96:111], v[192:195], v[184:187], v[96:111]
	s_waitcnt lgkmcnt(2)
	v_mfma_f32_32x32x16_bf16 v[80:95], v[196:199], v[160:163], v[80:95]
	v_mfma_f32_32x32x16_bf16 v[112:127], v[196:199], v[184:187], v[112:127]
	s_waitcnt lgkmcnt(1)
	v_mfma_f32_32x32x16_bf16 v[64:79], v[200:203], v[164:167], v[64:79]
	v_mfma_f32_32x32x16_bf16 v[96:111], v[200:203], v[188:191], v[96:111]
	s_waitcnt lgkmcnt(0)
	v_mfma_f32_32x32x16_bf16 v[80:95], v[204:207], v[164:167], v[80:95]
	v_mfma_f32_32x32x16_bf16 v[112:127], v[204:207], v[188:191], v[112:127]
	s_nop 7
	s_nop 7
	v_max3_f32 v248, v64, v65, v66
	v_max3_f32 v249, v80, v81, v82
	v_max3_f32 v250, v96, v97, v98
	v_max3_f32 v251, v112, v113, v114
	v_max3_f32 v248, v248, v67, v68
	v_max3_f32 v249, v249, v83, v84
	v_max3_f32 v250, v250, v99, v100
	v_max3_f32 v251, v251, v115, v116
	v_max3_f32 v248, v248, v69, v70
	v_max3_f32 v249, v249, v85, v86
	v_max3_f32 v250, v250, v101, v102
	v_max3_f32 v251, v251, v117, v118
	v_max3_f32 v248, v248, v71, v72
	v_max3_f32 v249, v249, v87, v88
	v_max3_f32 v250, v250, v103, v104
	v_max3_f32 v251, v251, v119, v120
	v_max3_f32 v248, v248, v73, v74
	v_max3_f32 v249, v249, v89, v90
	v_max3_f32 v250, v250, v105, v106
	v_max3_f32 v251, v251, v121, v122
	v_max3_f32 v248, v248, v75, v76
	v_max3_f32 v249, v249, v91, v92
	v_max3_f32 v250, v250, v107, v108
	v_max3_f32 v251, v251, v123, v124
	v_max3_f32 v248, v248, v77, v78
	v_max3_f32 v249, v249, v93, v94
	v_max3_f32 v250, v250, v109, v110
	v_max3_f32 v251, v251, v125, v126
	v_max_f32_e32 v248, v248, v79
	v_max_f32_e32 v249, v249, v95
	v_max_f32_e32 v250, v250, v111
	v_max_f32_e32 v251, v251, v127
	v_max3_f32 v253, v248, v249, v250
	v_max_f32_e32 v253, v253, v251
	v_mov_b32_e32 v252, v253
	s_nop 1
	v_permlane32_swap_b32_e32 v253, v252
	v_max_f32_e32 v253, v253, v252
	v_sub_f32_e32 v64, v64, v253
	v_sub_f32_e32 v65, v65, v253
	v_sub_f32_e32 v66, v66, v253
	v_sub_f32_e32 v67, v67, v253
	v_sub_f32_e32 v68, v68, v253
	v_sub_f32_e32 v69, v69, v253
	v_sub_f32_e32 v70, v70, v253
	v_sub_f32_e32 v71, v71, v253
	v_sub_f32_e32 v72, v72, v253
	v_sub_f32_e32 v73, v73, v253
	v_sub_f32_e32 v74, v74, v253
	v_sub_f32_e32 v75, v75, v253
	v_sub_f32_e32 v76, v76, v253
	v_sub_f32_e32 v77, v77, v253
	v_sub_f32_e32 v78, v78, v253
	v_sub_f32_e32 v79, v79, v253
	v_sub_f32_e32 v80, v80, v253
	v_sub_f32_e32 v81, v81, v253
	v_sub_f32_e32 v82, v82, v253
	v_sub_f32_e32 v83, v83, v253
	v_sub_f32_e32 v84, v84, v253
	v_sub_f32_e32 v85, v85, v253
	v_sub_f32_e32 v86, v86, v253
	v_sub_f32_e32 v87, v87, v253
	v_sub_f32_e32 v88, v88, v253
	v_sub_f32_e32 v89, v89, v253
	v_sub_f32_e32 v90, v90, v253
	v_sub_f32_e32 v91, v91, v253
	v_sub_f32_e32 v92, v92, v253
	v_sub_f32_e32 v93, v93, v253
	v_sub_f32_e32 v94, v94, v253
	v_sub_f32_e32 v95, v95, v253
	v_sub_f32_e32 v96, v96, v253
	v_sub_f32_e32 v97, v97, v253
	v_sub_f32_e32 v98, v98, v253
	v_sub_f32_e32 v99, v99, v253
	v_sub_f32_e32 v100, v100, v253
	v_sub_f32_e32 v101, v101, v253
	v_sub_f32_e32 v102, v102, v253
	v_sub_f32_e32 v103, v103, v253
	v_sub_f32_e32 v104, v104, v253
	v_sub_f32_e32 v105, v105, v253
	v_sub_f32_e32 v106, v106, v253
	v_sub_f32_e32 v107, v107, v253
	v_sub_f32_e32 v108, v108, v253
	v_sub_f32_e32 v109, v109, v253
	v_sub_f32_e32 v110, v110, v253
	v_sub_f32_e32 v111, v111, v253
	v_sub_f32_e32 v112, v112, v253
	v_sub_f32_e32 v113, v113, v253
	v_sub_f32_e32 v114, v114, v253
	v_sub_f32_e32 v115, v115, v253
	v_sub_f32_e32 v116, v116, v253
	v_sub_f32_e32 v117, v117, v253
	v_sub_f32_e32 v118, v118, v253
	v_sub_f32_e32 v119, v119, v253
	v_sub_f32_e32 v120, v120, v253
	v_sub_f32_e32 v121, v121, v253
	v_sub_f32_e32 v122, v122, v253
	v_sub_f32_e32 v123, v123, v253
	v_sub_f32_e32 v124, v124, v253
	v_sub_f32_e32 v125, v125, v253
	v_sub_f32_e32 v126, v126, v253
	v_sub_f32_e32 v127, v127, v253
	v_sub_f32_e32 v208, 0, v253
	v_sub_f32_e32 v209, 0, v253
	v_sub_f32_e32 v210, 0, v253
	v_sub_f32_e32 v211, 0, v253
	v_sub_f32_e32 v212, 0, v253
	v_sub_f32_e32 v213, 0, v253
	v_sub_f32_e32 v214, 0, v253
	v_sub_f32_e32 v215, 0, v253
	v_sub_f32_e32 v216, 0, v253
	v_sub_f32_e32 v217, 0, v253
	v_sub_f32_e32 v218, 0, v253
	v_sub_f32_e32 v219, 0, v253
	v_sub_f32_e32 v220, 0, v253
	v_sub_f32_e32 v221, 0, v253
	v_sub_f32_e32 v222, 0, v253
	v_sub_f32_e32 v223, 0, v253
	s_mov_b32 s68, 0
; template <int DQK>
; DI void attn_item(const bf16_t* __restrict__ Q, const bf16_t* __restrict__ Kp, const bf16_t* __restrict__ Vt, int q0, int nkeys,
;                   bf16_t* __restrict__ mix, int colbase, int b, char* smem) {
;     ...
;   for (int kt = 0; kt < nt; kt += 2) {
;     A_TILE(0)
;     A_WRITE(q, 1)
;     __syncthreads();
;     if (kt + 3 < nt) A_LOAD(q, (kt + 3) << 6)
.Lat2_loop_m:
	s_waitcnt vmcnt(0)
	ds_write_b128 v131, v[224:227] offset:13312
	ds_write_b128 v132, v[228:231] offset:13312
	ds_write_b128 v133, v[232:235] offset:13312
	ds_write_b64 v134, v[236:237] offset:35328
	ds_write_b64 v134, v[238:239] offset:35336
	ds_write_b64 v135, v[240:241] offset:35328
	ds_write_b64 v135, v[242:243] offset:35336
	s_add_u32 s1, s68, 2
	s_min_u32 s0, s1, 67
	s_mul_i32 s10, s0, 0x3000
	s_add_u32 s64, s60, s10
	s_addc_u32 s65, s61, 0
	s_lshl_b32 s0, s0, 7
	s_add_u32 s66, s62, s0
	s_addc_u32 s67, s63, 0
	global_load_dwordx4 v[224:227], v136, s[64:65]
	global_load_dwordx4 v[228:231], v137, s[64:65]
	global_load_dwordx4 v[232:235], v138, s[64:65]
	global_load_dwordx4 v[236:239], v139, s[66:67]
	global_load_dwordx4 v[240:243], v140, s[66:67]
	v_add_u32_e32 v248, 0x6800, v129
	v_add_u32_e32 v249, 0x6800, v130
	ds_read2_b64 v[192:195], v248 offset0:0 offset1:2
	ds_read2_b64 v[196:199], v249 offset0:0 offset1:2
	ds_read2_b64 v[200:203], v248 offset0:4 offset1:6
	ds_read2_b64 v[204:207], v249 offset0:4 offset1:6
	v_exp_f32_e32 v64, v64
	v_exp_f32_e32 v65, v65
	v_exp_f32_e32 v66, v66
	v_exp_f32_e32 v67, v67
	v_exp_f32_e32 v68, v68
	v_exp_f32_e32 v69, v69
	v_exp_f32_e32 v70, v70
	v_exp_f32_e32 v71, v71
	v_exp_f32_e32 v96, v96
	v_exp_f32_e32 v97, v97
	v_exp_f32_e32 v98, v98
	v_exp_f32_e32 v99, v99
	v_exp_f32_e32 v100, v100
	v_exp_f32_e32 v101, v101
	v_exp_f32_e32 v102, v102
	v_exp_f32_e32 v103, v103
	v_add_f32_e32 v244, v244, v64
	v_add_f32_e32 v245, v245, v65
	v_add_f32_e32 v244, v244, v66
	v_add_f32_e32 v245, v245, v67
	v_add_f32_e32 v244, v244, v68
	v_add_f32_e32 v245, v245, v69
	v_add_f32_e32 v244, v244, v70
	v_add_f32_e32 v245, v245, v71
	v_add_f32_e32 v246, v246, v96
	v_add_f32_e32 v247, v247, v97
	v_add_f32_e32 v246, v246, v98
	v_add_f32_e32 v247, v247, v99
	v_add_f32_e32 v246, v246, v100
	v_add_f32_e32 v247, v247, v101
	v_add_f32_e32 v246, v246, v102
	v_add_f32_e32 v247, v247, v103
	v_cvt_pk_bf16_f32 v64, v64, v65
	v_cvt_pk_bf16_f32 v65, v66, v67
	v_cvt_pk_bf16_f32 v66, v68, v69
	v_cvt_pk_bf16_f32 v67, v70, v71
	v_cvt_pk_bf16_f32 v96, v96, v97
	v_cvt_pk_bf16_f32 v97, v98, v99
	v_cvt_pk_bf16_f32 v98, v100, v101
	v_cvt_pk_bf16_f32 v99, v102, v103
	s_waitcnt lgkmcnt(3)
	v_mfma_f32_32x32x16_bf16 v[0:15], v[192:195], v[64:67], v[0:15]
	v_mfma_f32_32x32x16_bf16 v[32:47], v[192:195], v[96:99], v[32:47]
	ds_read2_b64 v[192:195], v248 offset0:8 offset1:10
	s_waitcnt lgkmcnt(3)
	v_mfma_f32_32x32x16_bf16 v[16:31], v[196:199], v[64:67], v[16:31]
	v_mfma_f32_32x32x16_bf16 v[48:63], v[196:199], v[96:99], v[48:63]
	ds_read2_b64 v[196:199], v249 offset0:8 offset1:10
	v_exp_f32_e32 v72, v72
	v_exp_f32_e32 v73, v73
	v_exp_f32_e32 v74, v74
	v_exp_f32_e32 v75, v75
	v_exp_f32_e32 v76, v76
	v_exp_f32_e32 v77, v77
	v_exp_f32_e32 v78, v78
	v_exp_f32_e32 v79, v79
	v_exp_f32_e32 v104, v104
	v_exp_f32_e32 v105, v105
	v_exp_f32_e32 v106, v106
	v_exp_f32_e32 v107, v107
	v_exp_f32_e32 v108, v108
	v_exp_f32_e32 v109, v109
	v_exp_f32_e32 v110, v110
	v_exp_f32_e32 v111, v111
	v_add_f32_e32 v244, v244, v72
	v_add_f32_e32 v245, v245, v73
	v_add_f32_e32 v244, v244, v74
	v_add_f32_e32 v245, v245, v75
	v_add_f32_e32 v244, v244, v76
	v_add_f32_e32 v245, v245, v77
	v_add_f32_e32 v244, v244, v78
	v_add_f32_e32 v245, v245, v79
	v_add_f32_e32 v246, v246, v104
	v_add_f32_e32 v247, v247, v105
	v_add_f32_e32 v246, v246, v106
	v_add_f32_e32 v247, v247, v107
	v_add_f32_e32 v246, v246, v108
	v_add_f32_e32 v247, v247, v109
	v_add_f32_e32 v246, v246, v110
	v_add_f32_e32 v247, v247, v111
	v_cvt_pk_bf16_f32 v68, v72, v73
	v_cvt_pk_bf16_f32 v69, v74, v75
	v_cvt_pk_bf16_f32 v70, v76, v77
	v_cvt_pk_bf16_f32 v71, v78, v79
	v_cvt_pk_bf16_f32 v100, v104, v105
	v_cvt_pk_bf16_f32 v101, v106, v107
	v_cvt_pk_bf16_f32 v102, v108, v109
	v_cvt_pk_bf16_f32 v103, v110, v111
	s_waitcnt lgkmcnt(3)
	v_mfma_f32_32x32x16_bf16 v[0:15], v[200:203], v[68:71], v[0:15]
	v_mfma_f32_32x32x16_bf16 v[32:47], v[200:203], v[100:103], v[32:47]
	ds_read2_b64 v[200:203], v248 offset0:12 offset1:14
	s_waitcnt lgkmcnt(3)
	v_mfma_f32_32x32x16_bf16 v[16:31], v[204:207], v[68:71], v[16:31]
	v_mfma_f32_32x32x16_bf16 v[48:63], v[204:207], v[100:103], v[48:63]
	ds_read2_b64 v[204:207], v249 offset0:12 offset1:14
	v_exp_f32_e32 v80, v80
	v_exp_f32_e32 v81, v81
	v_exp_f32_e32 v82, v82
	v_exp_f32_e32 v83, v83
	v_exp_f32_e32 v84, v84
	v_exp_f32_e32 v85, v85
	v_exp_f32_e32 v86, v86
	v_exp_f32_e32 v87, v87
	v_exp_f32_e32 v112, v112
	v_exp_f32_e32 v113, v113
	v_exp_f32_e32 v114, v114
	v_exp_f32_e32 v115, v115
	v_exp_f32_e32 v116, v116
	v_exp_f32_e32 v117, v117
	v_exp_f32_e32 v118, v118
	v_exp_f32_e32 v119, v119
	v_add_f32_e32 v244, v244, v80
	v_add_f32_e32 v245, v245, v81
	v_add_f32_e32 v244, v244, v82
	v_add_f32_e32 v245, v245, v83
	v_add_f32_e32 v244, v244, v84
	v_add_f32_e32 v245, v245, v85
	v_add_f32_e32 v244, v244, v86
	v_add_f32_e32 v245, v245, v87
	v_add_f32_e32 v246, v246, v112
	v_add_f32_e32 v247, v247, v113
	v_add_f32_e32 v246, v246, v114
	v_add_f32_e32 v247, v247, v115
	v_add_f32_e32 v246, v246, v116
	v_add_f32_e32 v247, v247, v117
	v_add_f32_e32 v246, v246, v118
	v_add_f32_e32 v247, v247, v119
	v_cvt_pk_bf16_f32 v72, v80, v81
	v_cvt_pk_bf16_f32 v73, v82, v83
	v_cvt_pk_bf16_f32 v74, v84, v85
	v_cvt_pk_bf16_f32 v75, v86, v87
	v_cvt_pk_bf16_f32 v104, v112, v113
	v_cvt_pk_bf16_f32 v105, v114, v115
	v_cvt_pk_bf16_f32 v106, v116, v117
	v_cvt_pk_bf16_f32 v107, v118, v119
	s_waitcnt lgkmcnt(3)
	v_mfma_f32_32x32x16_bf16 v[0:15], v[192:195], v[72:75], v[0:15]
	v_mfma_f32_32x32x16_bf16 v[32:47], v[192:195], v[104:107], v[32:47]
	s_waitcnt lgkmcnt(2)
	v_mfma_f32_32x32x16_bf16 v[16:31], v[196:199], v[72:75], v[16:31]
	v_mfma_f32_32x32x16_bf16 v[48:63], v[196:199], v[104:107], v[48:63]
	v_exp_f32_e32 v88, v88
	v_exp_f32_e32 v89, v89
	v_exp_f32_e32 v90, v90
	v_exp_f32_e32 v91, v91
	v_exp_f32_e32 v92, v92
	v_exp_f32_e32 v93, v93
	v_exp_f32_e32 v94, v94
	v_exp_f32_e32 v95, v95
	v_exp_f32_e32 v120, v120
	v_exp_f32_e32 v121, v121
	v_exp_f32_e32 v122, v122
	v_exp_f32_e32 v123, v123
	v_exp_f32_e32 v124, v124
	v_exp_f32_e32 v125, v125
	v_exp_f32_e32 v126, v126
	v_exp_f32_e32 v127, v127
	v_add_f32_e32 v244, v244, v88
	v_add_f32_e32 v245, v245, v89
	v_add_f32_e32 v244, v244, v90
	v_add_f32_e32 v245, v245, v91
	v_add_f32_e32 v244, v244, v92
	v_add_f32_e32 v245, v245, v93
	v_add_f32_e32 v244, v244, v94
	v_add_f32_e32 v245, v245, v95
	v_add_f32_e32 v246, v246, v120
	v_add_f32_e32 v247, v247, v121
	v_add_f32_e32 v246, v246, v122
	v_add_f32_e32 v247, v247, v123
	v_add_f32_e32 v246, v246, v124
	v_add_f32_e32 v247, v247, v125
	v_add_f32_e32 v246, v246, v126
	v_add_f32_e32 v247, v247, v127
	v_cvt_pk_bf16_f32 v76, v88, v89
	v_cvt_pk_bf16_f32 v77, v90, v91
	v_cvt_pk_bf16_f32 v78, v92, v93
	v_cvt_pk_bf16_f32 v79, v94, v95
	v_cvt_pk_bf16_f32 v108, v120, v121
	v_cvt_pk_bf16_f32 v109, v122, v123
	v_cvt_pk_bf16_f32 v110, v124, v125
	v_cvt_pk_bf16_f32 v111, v126, v127
	s_waitcnt lgkmcnt(1)
	v_mfma_f32_32x32x16_bf16 v[0:15], v[200:203], v[76:79], v[0:15]
	v_mfma_f32_32x32x16_bf16 v[32:47], v[200:203], v[108:111], v[32:47]
	s_waitcnt lgkmcnt(0)
	v_mfma_f32_32x32x16_bf16 v[16:31], v[204:207], v[76:79], v[16:31]
	v_mfma_f32_32x32x16_bf16 v[48:63], v[204:207], v[108:111], v[48:63]
	s_add_u32 s68, s68, 1
	s_waitcnt lgkmcnt(0)
	s_barrier
	ds_read_b128 v[192:195], v128 offset:13312
	ds_read_b128 v[196:199], v128 offset:19968
	ds_read_b128 v[200:203], v128 offset:13344
	ds_read_b128 v[204:207], v128 offset:20000
	s_waitcnt lgkmcnt(3)
	v_mfma_f32_32x32x16_bf16 v[64:79], v[192:195], v[144:147], v[208:223]
	v_mfma_f32_32x32x16_bf16 v[96:111], v[192:195], v[168:171], v[208:223]
	ds_read_b128 v[192:195], v128 offset:13376
	s_waitcnt lgkmcnt(3)
	v_mfma_f32_32x32x16_bf16 v[80:95], v[196:199], v[144:147], v[208:223]
	v_mfma_f32_32x32x16_bf16 v[112:127], v[196:199], v[168:171], v[208:223]
	ds_read_b128 v[196:199], v128 offset:20032
	s_waitcnt lgkmcnt(3)
	v_mfma_f32_32x32x16_bf16 v[64:79], v[200:203], v[148:151], v[64:79]
	v_mfma_f32_32x32x16_bf16 v[96:111], v[200:203], v[172:175], v[96:111]
	ds_read_b128 v[200:203], v128 offset:13408
	s_waitcnt lgkmcnt(3)
	v_mfma_f32_32x32x16_bf16 v[80:95], v[204:207], v[148:151], v[80:95]
	v_mfma_f32_32x32x16_bf16 v[112:127], v[204:207], v[172:175], v[112:127]
	ds_read_b128 v[204:207], v128 offset:20064
	s_waitcnt lgkmcnt(3)
	v_mfma_f32_32x32x16_bf16 v[64:79], v[192:195], v[152:155], v[64:79]
	v_mfma_f32_32x32x16_bf16 v[96:111], v[192:195], v[176:179], v[96:111]
	ds_read_b128 v[192:195], v128 offset:13440
	s_waitcnt lgkmcnt(3)
	v_mfma_f32_32x32x16_bf16 v[80:95], v[196:199], v[152:155], v[80:95]
	v_mfma_f32_32x32x16_bf16 v[112:127], v[196:199], v[176:179], v[112:127]
	ds_read_b128 v[196:199], v128 offset:20096
	s_waitcnt lgkmcnt(3)
	v_mfma_f32_32x32x16_bf16 v[64:79], v[200:203], v[156:159], v[64:79]
	v_mfma_f32_32x32x16_bf16 v[96:111], v[200:203], v[180:183], v[96:111]
	ds_read_b128 v[200:203], v128 offset:13472
	s_waitcnt lgkmcnt(3)
	v_mfma_f32_32x32x16_bf16 v[80:95], v[204:207], v[156:159], v[80:95]
	v_mfma_f32_32x32x16_bf16 v[112:127], v[204:207], v[180:183], v[112:127]
	ds_read_b128 v[204:207], v128 offset:20128
	s_waitcnt lgkmcnt(3)
	v_mfma_f32_32x32x16_bf16 v[64:79], v[192:195], v[160:163], v[64:79]
	v_mfma_f32_32x32x16_bf16 v[96:111], v[192:195], v[184:187], v[96:111]
	s_waitcnt lgkmcnt(2)
	v_mfma_f32_32x32x16_bf16 v[80:95], v[196:199], v[160:163], v[80:95]
	v_mfma_f32_32x32x16_bf16 v[112:127], v[196:199], v[184:187], v[112:127]
	s_waitcnt lgkmcnt(1)
	v_mfma_f32_32x32x16_bf16 v[64:79], v[200:203], v[164:167], v[64:79]
	v_mfma_f32_32x32x16_bf16 v[96:111], v[200:203], v[188:191], v[96:111]
	s_waitcnt lgkmcnt(0)
	v_mfma_f32_32x32x16_bf16 v[80:95], v[204:207], v[164:167], v[80:95]
	v_mfma_f32_32x32x16_bf16 v[112:127], v[204:207], v[188:191], v[112:127]
	s_waitcnt vmcnt(0)
	ds_write_b128 v131, v[224:227] offset:0
	ds_write_b128 v132, v[228:231] offset:0
	ds_write_b128 v133, v[232:235] offset:0
	ds_write_b64 v134, v[236:237] offset:26624
	ds_write_b64 v134, v[238:239] offset:26632
	ds_write_b64 v135, v[240:241] offset:26624
	ds_write_b64 v135, v[242:243] offset:26632
	s_add_u32 s1, s68, 2
	s_min_u32 s0, s1, 67
	s_mul_i32 s10, s0, 0x3000
	s_add_u32 s64, s60, s10
	s_addc_u32 s65, s61, 0
	s_lshl_b32 s0, s0, 7
	s_add_u32 s66, s62, s0
	s_addc_u32 s67, s63, 0
	global_load_dwordx4 v[224:227], v136, s[64:65]
	global_load_dwordx4 v[228:231], v137, s[64:65]
	global_load_dwordx4 v[232:235], v138, s[64:65]
	global_load_dwordx4 v[236:239], v139, s[66:67]
	global_load_dwordx4 v[240:243], v140, s[66:67]
	v_add_u32_e32 v248, 0x8a00, v129
	v_add_u32_e32 v249, 0x8a00, v130
	ds_read2_b64 v[192:195], v248 offset0:0 offset1:2
	ds_read2_b64 v[196:199], v249 offset0:0 offset1:2
	ds_read2_b64 v[200:203], v248 offset0:4 offset1:6
	ds_read2_b64 v[204:207], v249 offset0:4 offset1:6
	v_exp_f32_e32 v64, v64
	v_exp_f32_e32 v65, v65
	v_exp_f32_e32 v66, v66
	v_exp_f32_e32 v67, v67
	v_exp_f32_e32 v68, v68
	v_exp_f32_e32 v69, v69
	v_exp_f32_e32 v70, v70
	v_exp_f32_e32 v71, v71
	v_exp_f32_e32 v96, v96
	v_exp_f32_e32 v97, v97
	v_exp_f32_e32 v98, v98
	v_exp_f32_e32 v99, v99
	v_exp_f32_e32 v100, v100
	v_exp_f32_e32 v101, v101
	v_exp_f32_e32 v102, v102
	v_exp_f32_e32 v103, v103
	v_add_f32_e32 v244, v244, v64
	v_add_f32_e32 v245, v245, v65
	v_add_f32_e32 v244, v244, v66
	v_add_f32_e32 v245, v245, v67
	v_add_f32_e32 v244, v244, v68
	v_add_f32_e32 v245, v245, v69
	v_add_f32_e32 v244, v244, v70
	v_add_f32_e32 v245, v245, v71
	v_add_f32_e32 v246, v246, v96
	v_add_f32_e32 v247, v247, v97
	v_add_f32_e32 v246, v246, v98
	v_add_f32_e32 v247, v247, v99
	v_add_f32_e32 v246, v246, v100
	v_add_f32_e32 v247, v247, v101
	v_add_f32_e32 v246, v246, v102
	v_add_f32_e32 v247, v247, v103
	v_cvt_pk_bf16_f32 v64, v64, v65
	v_cvt_pk_bf16_f32 v65, v66, v67
	v_cvt_pk_bf16_f32 v66, v68, v69
	v_cvt_pk_bf16_f32 v67, v70, v71
	v_cvt_pk_bf16_f32 v96, v96, v97
	v_cvt_pk_bf16_f32 v97, v98, v99
	v_cvt_pk_bf16_f32 v98, v100, v101
	v_cvt_pk_bf16_f32 v99, v102, v103
	s_waitcnt lgkmcnt(3)
	v_mfma_f32_32x32x16_bf16 v[0:15], v[192:195], v[64:67], v[0:15]
	v_mfma_f32_32x32x16_bf16 v[32:47], v[192:195], v[96:99], v[32:47]
	ds_read2_b64 v[192:195], v248 offset0:8 offset1:10
	s_waitcnt lgkmcnt(3)
	v_mfma_f32_32x32x16_bf16 v[16:31], v[196:199], v[64:67], v[16:31]
	v_mfma_f32_32x32x16_bf16 v[48:63], v[196:199], v[96:99], v[48:63]
	ds_read2_b64 v[196:199], v249 offset0:8 offset1:10
	v_exp_f32_e32 v72, v72
	v_exp_f32_e32 v73, v73
	v_exp_f32_e32 v74, v74
	v_exp_f32_e32 v75, v75
	v_exp_f32_e32 v76, v76
	v_exp_f32_e32 v77, v77
	v_exp_f32_e32 v78, v78
	v_exp_f32_e32 v79, v79
	v_exp_f32_e32 v104, v104
	v_exp_f32_e32 v105, v105
	v_exp_f32_e32 v106, v106
	v_exp_f32_e32 v107, v107
	v_exp_f32_e32 v108, v108
	v_exp_f32_e32 v109, v109
	v_exp_f32_e32 v110, v110
	v_exp_f32_e32 v111, v111
	v_add_f32_e32 v244, v244, v72
	v_add_f32_e32 v245, v245, v73
	v_add_f32_e32 v244, v244, v74
	v_add_f32_e32 v245, v245, v75
	v_add_f32_e32 v244, v244, v76
	v_add_f32_e32 v245, v245, v77
	v_add_f32_e32 v244, v244, v78
	v_add_f32_e32 v245, v245, v79
	v_add_f32_e32 v246, v246, v104
	v_add_f32_e32 v247, v247, v105
	v_add_f32_e32 v246, v246, v106
	v_add_f32_e32 v247, v247, v107
	v_add_f32_e32 v246, v246, v108
	v_add_f32_e32 v247, v247, v109
	v_add_f32_e32 v246, v246, v110
	v_add_f32_e32 v247, v247, v111
	v_cvt_pk_bf16_f32 v68, v72, v73
	v_cvt_pk_bf16_f32 v69, v74, v75
	v_cvt_pk_bf16_f32 v70, v76, v77
	v_cvt_pk_bf16_f32 v71, v78, v79
	v_cvt_pk_bf16_f32 v100, v104, v105
	v_cvt_pk_bf16_f32 v101, v106, v107
	v_cvt_pk_bf16_f32 v102, v108, v109
	v_cvt_pk_bf16_f32 v103, v110, v111
	s_waitcnt lgkmcnt(3)
	v_mfma_f32_32x32x16_bf16 v[0:15], v[200:203], v[68:71], v[0:15]
	v_mfma_f32_32x32x16_bf16 v[32:47], v[200:203], v[100:103], v[32:47]
	ds_read2_b64 v[200:203], v248 offset0:12 offset1:14
	s_waitcnt lgkmcnt(3)
	v_mfma_f32_32x32x16_bf16 v[16:31], v[204:207], v[68:71], v[16:31]
	v_mfma_f32_32x32x16_bf16 v[48:63], v[204:207], v[100:103], v[48:63]
	ds_read2_b64 v[204:207], v249 offset0:12 offset1:14
	v_exp_f32_e32 v80, v80
	v_exp_f32_e32 v81, v81
	v_exp_f32_e32 v82, v82
	v_exp_f32_e32 v83, v83
	v_exp_f32_e32 v84, v84
	v_exp_f32_e32 v85, v85
	v_exp_f32_e32 v86, v86
	v_exp_f32_e32 v87, v87
	v_exp_f32_e32 v112, v112
	v_exp_f32_e32 v113, v113
	v_exp_f32_e32 v114, v114
	v_exp_f32_e32 v115, v115
	v_exp_f32_e32 v116, v116
	v_exp_f32_e32 v117, v117
	v_exp_f32_e32 v118, v118
	v_exp_f32_e32 v119, v119
	v_add_f32_e32 v244, v244, v80
	v_add_f32_e32 v245, v245, v81
	v_add_f32_e32 v244, v244, v82
	v_add_f32_e32 v245, v245, v83
	v_add_f32_e32 v244, v244, v84
	v_add_f32_e32 v245, v245, v85
	v_add_f32_e32 v244, v244, v86
	v_add_f32_e32 v245, v245, v87
	v_add_f32_e32 v246, v246, v112
	v_add_f32_e32 v247, v247, v113
	v_add_f32_e32 v246, v246, v114
	v_add_f32_e32 v247, v247, v115
	v_add_f32_e32 v246, v246, v116
	v_add_f32_e32 v247, v247, v117
	v_add_f32_e32 v246, v246, v118
	v_add_f32_e32 v247, v247, v119
	v_cvt_pk_bf16_f32 v72, v80, v81
	v_cvt_pk_bf16_f32 v73, v82, v83
	v_cvt_pk_bf16_f32 v74, v84, v85
	v_cvt_pk_bf16_f32 v75, v86, v87
	v_cvt_pk_bf16_f32 v104, v112, v113
	v_cvt_pk_bf16_f32 v105, v114, v115
	v_cvt_pk_bf16_f32 v106, v116, v117
	v_cvt_pk_bf16_f32 v107, v118, v119
	s_waitcnt lgkmcnt(3)
	v_mfma_f32_32x32x16_bf16 v[0:15], v[192:195], v[72:75], v[0:15]
	v_mfma_f32_32x32x16_bf16 v[32:47], v[192:195], v[104:107], v[32:47]
	s_waitcnt lgkmcnt(2)
	v_mfma_f32_32x32x16_bf16 v[16:31], v[196:199], v[72:75], v[16:31]
	v_mfma_f32_32x32x16_bf16 v[48:63], v[196:199], v[104:107], v[48:63]
	v_exp_f32_e32 v88, v88
	v_exp_f32_e32 v89, v89
	v_exp_f32_e32 v90, v90
	v_exp_f32_e32 v91, v91
	v_exp_f32_e32 v92, v92
	v_exp_f32_e32 v93, v93
	v_exp_f32_e32 v94, v94
	v_exp_f32_e32 v95, v95
	v_exp_f32_e32 v120, v120
	v_exp_f32_e32 v121, v121
	v_exp_f32_e32 v122, v122
	v_exp_f32_e32 v123, v123
	v_exp_f32_e32 v124, v124
	v_exp_f32_e32 v125, v125
	v_exp_f32_e32 v126, v126
	v_exp_f32_e32 v127, v127
	v_add_f32_e32 v244, v244, v88
	v_add_f32_e32 v245, v245, v89
	v_add_f32_e32 v244, v244, v90
	v_add_f32_e32 v245, v245, v91
	v_add_f32_e32 v244, v244, v92
	v_add_f32_e32 v245, v245, v93
	v_add_f32_e32 v244, v244, v94
	v_add_f32_e32 v245, v245, v95
	v_add_f32_e32 v246, v246, v120
	v_add_f32_e32 v247, v247, v121
	v_add_f32_e32 v246, v246, v122
	v_add_f32_e32 v247, v247, v123
	v_add_f32_e32 v246, v246, v124
	v_add_f32_e32 v247, v247, v125
	v_add_f32_e32 v246, v246, v126
	v_add_f32_e32 v247, v247, v127
	v_cvt_pk_bf16_f32 v76, v88, v89
	v_cvt_pk_bf16_f32 v77, v90, v91
	v_cvt_pk_bf16_f32 v78, v92, v93
	v_cvt_pk_bf16_f32 v79, v94, v95
	v_cvt_pk_bf16_f32 v108, v120, v121
	v_cvt_pk_bf16_f32 v109, v122, v123
	v_cvt_pk_bf16_f32 v110, v124, v125
	v_cvt_pk_bf16_f32 v111, v126, v127
	s_waitcnt lgkmcnt(1)
	v_mfma_f32_32x32x16_bf16 v[0:15], v[200:203], v[76:79], v[0:15]
	v_mfma_f32_32x32x16_bf16 v[32:47], v[200:203], v[108:111], v[32:47]
	s_waitcnt lgkmcnt(0)
	v_mfma_f32_32x32x16_bf16 v[16:31], v[204:207], v[76:79], v[16:31]
	v_mfma_f32_32x32x16_bf16 v[48:63], v[204:207], v[108:111], v[48:63]
	s_add_u32 s68, s68, 1
	s_waitcnt lgkmcnt(0)
	s_barrier
; DI float xhalf_sum(float x) { auto r = __builtin_amdgcn_permlane32_swap(__float_as_uint(x), __float_as_uint(x), false, false); return __uint_as_float(r[0]) + __uint_as_float(r[1]); }
; template <int DQK>
; DI void attn_item(const bf16_t* __restrict__ Q, const bf16_t* __restrict__ Kp, const bf16_t* __restrict__ Vt, int q0, int nkeys,
;                   bf16_t* __restrict__ mix, int colbase, int b, char* smem) {
;     ...
;   l = xhalf_sum(l);
;   const float inv = 1.0f / l;
	ds_read_b128 v[192:195], v128 offset:0
	ds_read_b128 v[196:199], v128 offset:6656
	ds_read_b128 v[200:203], v128 offset:32
	ds_read_b128 v[204:207], v128 offset:6688
	s_waitcnt lgkmcnt(3)
	v_mfma_f32_32x32x16_bf16 v[64:79], v[192:195], v[144:147], v[208:223]
	v_mfma_f32_32x32x16_bf16 v[96:111], v[192:195], v[168:171], v[208:223]
	ds_read_b128 v[192:195], v128 offset:64
	s_waitcnt lgkmcnt(3)
	v_mfma_f32_32x32x16_bf16 v[80:95], v[196:199], v[144:147], v[208:223]
	v_mfma_f32_32x32x16_bf16 v[112:127], v[196:199], v[168:171], v[208:223]
	ds_read_b128 v[196:199], v128 offset:6720
	s_waitcnt lgkmcnt(3)
	v_mfma_f32_32x32x16_bf16 v[64:79], v[200:203], v[148:151], v[64:79]
	v_mfma_f32_32x32x16_bf16 v[96:111], v[200:203], v[172:175], v[96:111]
	ds_read_b128 v[200:203], v128 offset:96
	s_waitcnt lgkmcnt(3)
	v_mfma_f32_32x32x16_bf16 v[80:95], v[204:207], v[148:151], v[80:95]
	v_mfma_f32_32x32x16_bf16 v[112:127], v[204:207], v[172:175], v[112:127]
	ds_read_b128 v[204:207], v128 offset:6752
	s_waitcnt lgkmcnt(3)
	v_mfma_f32_32x32x16_bf16 v[64:79], v[192:195], v[152:155], v[64:79]
	v_mfma_f32_32x32x16_bf16 v[96:111], v[192:195], v[176:179], v[96:111]
	ds_read_b128 v[192:195], v128 offset:128
	s_waitcnt lgkmcnt(3)
	v_mfma_f32_32x32x16_bf16 v[80:95], v[196:199], v[152:155], v[80:95]
	v_mfma_f32_32x32x16_bf16 v[112:127], v[196:199], v[176:179], v[112:127]
	ds_read_b128 v[196:199], v128 offset:6784
	s_waitcnt lgkmcnt(3)
	v_mfma_f32_32x32x16_bf16 v[64:79], v[200:203], v[156:159], v[64:79]
	v_mfma_f32_32x32x16_bf16 v[96:111], v[200:203], v[180:183], v[96:111]
	ds_read_b128 v[200:203], v128 offset:160
	s_waitcnt lgkmcnt(3)
	v_mfma_f32_32x32x16_bf16 v[80:95], v[204:207], v[156:159], v[80:95]
	v_mfma_f32_32x32x16_bf16 v[112:127], v[204:207], v[180:183], v[112:127]
	ds_read_b128 v[204:207], v128 offset:6816
	s_waitcnt lgkmcnt(3)
	v_mfma_f32_32x32x16_bf16 v[64:79], v[192:195], v[160:163], v[64:79]
	v_mfma_f32_32x32x16_bf16 v[96:111], v[192:195], v[184:187], v[96:111]
	s_waitcnt lgkmcnt(2)
	v_mfma_f32_32x32x16_bf16 v[80:95], v[196:199], v[160:163], v[80:95]
	v_mfma_f32_32x32x16_bf16 v[112:127], v[196:199], v[184:187], v[112:127]
	s_waitcnt lgkmcnt(1)
	v_mfma_f32_32x32x16_bf16 v[64:79], v[200:203], v[164:167], v[64:79]
	v_mfma_f32_32x32x16_bf16 v[96:111], v[200:203], v[188:191], v[96:111]
	s_waitcnt lgkmcnt(0)
	v_mfma_f32_32x32x16_bf16 v[80:95], v[204:207], v[164:167], v[80:95]
	v_mfma_f32_32x32x16_bf16 v[112:127], v[204:207], v[188:191], v[112:127]
	s_cmp_lt_u32 s68, 68
	s_cbranch_scc1 .Lat2_loop_m
	s_waitcnt vmcnt(0)
	s_nop 7
	s_nop 7
	v_add_f32_e32 v244, v244, v245
	v_add_f32_e32 v246, v246, v247
	v_mov_b32_e32 v248, v244
	v_mov_b32_e32 v249, v246
	s_nop 1
	v_permlane32_swap_b32_e32 v244, v248
	v_permlane32_swap_b32_e32 v246, v249
	v_add_f32_e32 v244, v244, v248
	v_add_f32_e32 v246, v246, v249
	v_mov_b32_e32 v248, 0
	v_fmac_f32_e32 v248, 0, v0
	v_fmac_f32_e32 v248, 0, v1
	v_fmac_f32_e32 v248, 0, v2
	v_fmac_f32_e32 v248, 0, v3
	v_fmac_f32_e32 v248, 0, v4
	v_fmac_f32_e32 v248, 0, v5
	v_fmac_f32_e32 v248, 0, v6
	v_fmac_f32_e32 v248, 0, v7
	v_fmac_f32_e32 v248, 0, v8
	v_fmac_f32_e32 v248, 0, v9
	v_fmac_f32_e32 v248, 0, v10
	v_fmac_f32_e32 v248, 0, v11
	v_fmac_f32_e32 v248, 0, v12
	v_fmac_f32_e32 v248, 0, v13
	v_fmac_f32_e32 v248, 0, v14
	v_fmac_f32_e32 v248, 0, v15
	v_fmac_f32_e32 v248, 0, v16
	v_fmac_f32_e32 v248, 0, v17
	v_fmac_f32_e32 v248, 0, v18
	v_fmac_f32_e32 v248, 0, v19
	v_fmac_f32_e32 v248, 0, v20
	v_fmac_f32_e32 v248, 0, v21
	v_fmac_f32_e32 v248, 0, v22
	v_fmac_f32_e32 v248, 0, v23
	v_fmac_f32_e32 v248, 0, v24
	v_fmac_f32_e32 v248, 0, v25
	v_fmac_f32_e32 v248, 0, v26
	v_fmac_f32_e32 v248, 0, v27
	v_fmac_f32_e32 v248, 0, v28
	v_fmac_f32_e32 v248, 0, v29
	v_fmac_f32_e32 v248, 0, v30
	v_fmac_f32_e32 v248, 0, v31
	v_fmac_f32_e32 v248, 0, v32
	v_fmac_f32_e32 v248, 0, v33
	v_fmac_f32_e32 v248, 0, v34
	v_fmac_f32_e32 v248, 0, v35
	v_fmac_f32_e32 v248, 0, v36
	v_fmac_f32_e32 v248, 0, v37
	v_fmac_f32_e32 v248, 0, v38
	v_fmac_f32_e32 v248, 0, v39
	v_fmac_f32_e32 v248, 0, v40
	v_fmac_f32_e32 v248, 0, v41
	v_fmac_f32_e32 v248, 0, v42
	v_fmac_f32_e32 v248, 0, v43
	v_fmac_f32_e32 v248, 0, v44
	v_fmac_f32_e32 v248, 0, v45
	v_fmac_f32_e32 v248, 0, v46
	v_fmac_f32_e32 v248, 0, v47
	v_fmac_f32_e32 v248, 0, v48
	v_fmac_f32_e32 v248, 0, v49
	v_fmac_f32_e32 v248, 0, v50
	v_fmac_f32_e32 v248, 0, v51
	v_fmac_f32_e32 v248, 0, v52
	v_fmac_f32_e32 v248, 0, v53
	v_fmac_f32_e32 v248, 0, v54
	v_fmac_f32_e32 v248, 0, v55
	v_fmac_f32_e32 v248, 0, v56
	v_fmac_f32_e32 v248, 0, v57
	v_fmac_f32_e32 v248, 0, v58
	v_fmac_f32_e32 v248, 0, v59
	v_fmac_f32_e32 v248, 0, v60
	v_fmac_f32_e32 v248, 0, v61
	v_fmac_f32_e32 v248, 0, v62
	v_fmac_f32_e32 v248, 0, v63
	v_mov_b32_e32 v249, 0x71800000
	v_mov_b32_e32 v250, 0x21800000
	v_cmp_neq_f32_e32 vcc, 0, v248
	s_mov_b64 s[44:45], vcc
	v_cmp_nlt_f32_e32 vcc, v244, v249
	s_or_b64 s[44:45], vcc, s[44:45]
	v_cmp_ngt_f32_e32 vcc, v244, v250
	s_or_b64 s[44:45], vcc, s[44:45]
	v_cmp_nlt_f32_e32 vcc, v246, v249
	s_or_b64 s[44:45], vcc, s[44:45]
	v_cmp_ngt_f32_e32 vcc, v246, v250
	s_or_b64 s[44:45], vcc, s[44:45]
	s_cmp_lg_u64 s[44:45], 0
	s_cselect_b32 s0, 1, 0
	v_mov_b32_e32 v250, s0
	s_lshl_b32 s1, s57, 2
	s_add_u32 s1, s1, 0x13400
	v_mov_b32_e32 v251, s1
	v_mov_b32_e32 v252, 0x13400
	ds_write_b32 v251, v250
	s_waitcnt lgkmcnt(0)
	s_barrier
; DI unsigned pack2(float lo, float hi) { f32x2_t v = {lo, hi}; bf16x2_t r = __builtin_convertvector(v, bf16x2_t); return __builtin_bit_cast(unsigned, r); }
; DI float xhalf_sum(float x) { auto r = __builtin_amdgcn_permlane32_swap(__float_as_uint(x), __float_as_uint(x), false, false); return __uint_as_float(r[0]) + __uint_as_float(r[1]); }
; template <int DQK>
; DI void attn_item(const bf16_t* __restrict__ Q, const bf16_t* __restrict__ Kp, const bf16_t* __restrict__ Vt, int q0, int nkeys,
;                   bf16_t* __restrict__ mix, int colbase, int b, char* smem) {
;     ...
;   l = xhalf_sum(l);
;   const float inv = 1.0f / l;
;   const int kp = q0 + wave * 32 + r;
;   bf16_t* orow = mix + (size_t)row_of(b, kp) * D + colbase;
; #pragma unroll
;   for (int g = 0; g < 4; ++g) {
;     uint2 w0, w1;
;     w0.x = pack2(o0[4 * g] * inv, o0[4 * g + 1] * inv); w0.y = pack2(o0[4 * g + 2] * inv, o0[4 * g + 3] * inv);
;     w1.x = pack2(o1[4 * g] * inv, o1[4 * g + 1] * inv); w1.y = pack2(o1[4 * g + 2] * inv, o1[4 * g + 3] * inv);
;     *(uint2*)(orow + 8 * g + 4 * h) = w0;
;     *(uint2*)(orow + 32 + 8 * g + 4 * h) = w1;
;   }
	ds_read_b128 v[192:195], v252
	s_waitcnt lgkmcnt(0)
	v_or3_b32 v250, v192, v193, v194
	v_or_b32_e32 v250, v250, v195
	s_nop 0
	v_readfirstlane_b32 s0, v250
	s_nop 3
	s_cmp_eq_u32 s0, 0
	s_cbranch_scc0 .Lat2_fallback
	v_rcp_f32_e32 v248, v244
	v_rcp_f32_e32 v249, v246
	s_nop 0
	v_mul_f32_e32 v64, v0, v248
	v_mul_f32_e32 v65, v1, v248
	v_mul_f32_e32 v66, v2, v248
	v_mul_f32_e32 v67, v3, v248
	v_cvt_pk_bf16_f32 v192, v64, v65
	v_cvt_pk_bf16_f32 v193, v66, v67
	global_store_dwordx2 v141, v[192:193], s[72:73] offset:0
	v_mul_f32_e32 v64, v16, v248
	v_mul_f32_e32 v65, v17, v248
	v_mul_f32_e32 v66, v18, v248
	v_mul_f32_e32 v67, v19, v248
	v_cvt_pk_bf16_f32 v194, v64, v65
	v_cvt_pk_bf16_f32 v195, v66, v67
	global_store_dwordx2 v142, v[194:195], s[72:73] offset:0
	v_mul_f32_e32 v64, v4, v248
	v_mul_f32_e32 v65, v5, v248
	v_mul_f32_e32 v66, v6, v248
	v_mul_f32_e32 v67, v7, v248
	v_cvt_pk_bf16_f32 v196, v64, v65
	v_cvt_pk_bf16_f32 v197, v66, v67
	global_store_dwordx2 v141, v[196:197], s[72:73] offset:16
	v_mul_f32_e32 v64, v20, v248
	v_mul_f32_e32 v65, v21, v248
	v_mul_f32_e32 v66, v22, v248
	v_mul_f32_e32 v67, v23, v248
	v_cvt_pk_bf16_f32 v198, v64, v65
	v_cvt_pk_bf16_f32 v199, v66, v67
	global_store_dwordx2 v142, v[198:199], s[72:73] offset:16
	v_mul_f32_e32 v64, v8, v248
	v_mul_f32_e32 v65, v9, v248
	v_mul_f32_e32 v66, v10, v248
	v_mul_f32_e32 v67, v11, v248
	v_cvt_pk_bf16_f32 v200, v64, v65
	v_cvt_pk_bf16_f32 v201, v66, v67
	global_store_dwordx2 v141, v[200:201], s[72:73] offset:32
	v_mul_f32_e32 v64, v24, v248
	v_mul_f32_e32 v65, v25, v248
	v_mul_f32_e32 v66, v26, v248
	v_mul_f32_e32 v67, v27, v248
	v_cvt_pk_bf16_f32 v202, v64, v65
	v_cvt_pk_bf16_f32 v203, v66, v67
	global_store_dwordx2 v142, v[202:203], s[72:73] offset:32
	v_mul_f32_e32 v64, v12, v248
	v_mul_f32_e32 v65, v13, v248
	v_mul_f32_e32 v66, v14, v248
	v_mul_f32_e32 v67, v15, v248
	v_cvt_pk_bf16_f32 v204, v64, v65
	v_cvt_pk_bf16_f32 v205, v66, v67
	global_store_dwordx2 v141, v[204:205], s[72:73] offset:48
	v_mul_f32_e32 v64, v28, v248
	v_mul_f32_e32 v65, v29, v248
	v_mul_f32_e32 v66, v30, v248
	v_mul_f32_e32 v67, v31, v248
	v_cvt_pk_bf16_f32 v206, v64, v65
	v_cvt_pk_bf16_f32 v207, v66, v67
	global_store_dwordx2 v142, v[206:207], s[72:73] offset:48
	v_mul_f32_e32 v64, v32, v249
	v_mul_f32_e32 v65, v33, v249
	v_mul_f32_e32 v66, v34, v249
	v_mul_f32_e32 v67, v35, v249
	v_cvt_pk_bf16_f32 v192, v64, v65
	v_cvt_pk_bf16_f32 v193, v66, v67
	global_store_dwordx2 v141, v[192:193], s[76:77] offset:0
	v_mul_f32_e32 v64, v48, v249
	v_mul_f32_e32 v65, v49, v249
	v_mul_f32_e32 v66, v50, v249
	v_mul_f32_e32 v67, v51, v249
	v_cvt_pk_bf16_f32 v194, v64, v65
	v_cvt_pk_bf16_f32 v195, v66, v67
	global_store_dwordx2 v142, v[194:195], s[76:77] offset:0
	v_mul_f32_e32 v64, v36, v249
	v_mul_f32_e32 v65, v37, v249
	v_mul_f32_e32 v66, v38, v249
	v_mul_f32_e32 v67, v39, v249
	v_cvt_pk_bf16_f32 v196, v64, v65
	v_cvt_pk_bf16_f32 v197, v66, v67
	global_store_dwordx2 v141, v[196:197], s[76:77] offset:16
	v_mul_f32_e32 v64, v52, v249
	v_mul_f32_e32 v65, v53, v249
	v_mul_f32_e32 v66, v54, v249
	v_mul_f32_e32 v67, v55, v249
	v_cvt_pk_bf16_f32 v198, v64, v65
	v_cvt_pk_bf16_f32 v199, v66, v67
	global_store_dwordx2 v142, v[198:199], s[76:77] offset:16
	v_mul_f32_e32 v64, v40, v249
	v_mul_f32_e32 v65, v41, v249
	v_mul_f32_e32 v66, v42, v249
	v_mul_f32_e32 v67, v43, v249
	v_cvt_pk_bf16_f32 v200, v64, v65
	v_cvt_pk_bf16_f32 v201, v66, v67
	global_store_dwordx2 v141, v[200:201], s[76:77] offset:32
	v_mul_f32_e32 v64, v56, v249
	v_mul_f32_e32 v65, v57, v249
	v_mul_f32_e32 v66, v58, v249
	v_mul_f32_e32 v67, v59, v249
	v_cvt_pk_bf16_f32 v202, v64, v65
	v_cvt_pk_bf16_f32 v203, v66, v67
	global_store_dwordx2 v142, v[202:203], s[76:77] offset:32
	v_mul_f32_e32 v64, v44, v249
	v_mul_f32_e32 v65, v45, v249
	v_mul_f32_e32 v66, v46, v249
	v_mul_f32_e32 v67, v47, v249
	v_cvt_pk_bf16_f32 v204, v64, v65
	v_cvt_pk_bf16_f32 v205, v66, v67
	global_store_dwordx2 v141, v[204:205], s[76:77] offset:48
	v_mul_f32_e32 v64, v60, v249
	v_mul_f32_e32 v65, v61, v249
	v_mul_f32_e32 v66, v62, v249
	v_mul_f32_e32 v67, v63, v249
	v_cvt_pk_bf16_f32 v206, v64, v65
	v_cvt_pk_bf16_f32 v207, v66, v67
	global_store_dwordx2 v142, v[206:207], s[76:77] offset:48

; DI int get_tid() { int t = threadIdx.x; asm volatile("" : "+v"(t)); return t; }
; template <int DQK>
; DI void attn_item(const bf16_t* __restrict__ Q, const bf16_t* __restrict__ Kp, const bf16_t* __restrict__ Vt, int q0, int nkeys,
;                   bf16_t* __restrict__ mix, int colbase, int b, char* smem) {
;     ...
;   const int tid = get_tid(), lane = tid & 63, wave = tid >> 6, r = lane & 31, h = lane >> 5;
;   bf16x8 qf[NSTEP];
;   {
;     const bf16_t* qr = Q + (size_t)(q0 + wave * 32 + r) * DQK + 8 * h;
; #pragma unroll
;     for (int s = 0; s < NSTEP; ++s) qf[s] = *(const bf16x8*)(qr + 16 * s);
;   }
;   const int kid0 = tid, kid1 = tid + 256, kid2 = tid + 512;
;   const int kgo0 = (kid0 / KCH) * DQK + (kid0 % KCH) * 8, kgo1 = (kid1 / KCH) * DQK + (kid1 % KCH) * 8, kgo2 = (kid2 / KCH) * DQK + (kid2 % KCH) * 8;
;   const int kso0 = (kid0 / KCH) * KROW + (kid0 % KCH) * 8, kso1 = (kid1 / KCH) * KROW + (kid1 % KCH) * 8, kso2 = (kid2 / KCH) * KROW + (kid2 % KCH) * 8;
;   const int vrow0 = tid >> 3, vcc = (tid & 7) * 8;
;   const bf16_t* Vg0 = Vt + (size_t)vrow0 * NKEY + vcc;
;   const bf16_t* Vg1 = Vt + (size_t)(vrow0 + 32) * NKEY + vcc;
;   const int vso0 = vrow0 * VROW + vcc, vso1 = (vrow0 + 32) * VROW + vcc;
;   uint4 pk0, pk1, pk2, pv0, pv1, qk0, qk1, qk2, qv0, qv1;
;   pk2 = make_uint4(0, 0, 0, 0); qk2 = pk2;
;     ...
;   f32x16 o0, o1;
; #pragma unroll
;   for (int i = 0; i < 16; ++i) { o0[i] = 0.f; o1[i] = 0.f; }
;     ...
;   const int nt = nkeys >> 6;
;   A_LOAD(p, 0)
;   A_LOAD(q, 64)
;   A_WRITE(p, 0)
;   __syncthreads();
;   if (nt > 2) A_LOAD(p, 128)
.Lat2_fallback:
	s_mov_b32 s75, 0
	v_and_b32_e32 v253, 31, v143
	v_bfe_u32 v140, v143, 5, 1
.Lat2_fb_loop:
	s_lshl_b32 s11, s54, 12
	s_add_u32 s11, s11, s56
	s_sub_u32 s11, s11, 256
	s_lshl_b32 s28, s57, 5
	s_add_u32 s11, s11, s28
	v_add_u32_e32 v252, s11, v253
	v_lshlrev_b32_e32 v252, 6, v252
	v_lshl_add_u32 v252, v140, 3, v252
	s_cmp_eq_u32 s53, 1
	s_cbranch_scc1 .Lat_mla_1
	s_mul_i32 s11, s54, 6
	s_add_u32 s11, s11, s55
	s_mul_i32 s28, s11, 0x88000
	s_add_u32 s28, s28, 0x7f80000
	s_add_u32 s58, s24, s28
	s_addc_u32 s59, s25, 0
	s_mul_i32 s29, s55, 43
	s_lshr_b32 s29, s29, 7
	s_lshl_b32 s11, s54, 1
	s_add_u32 s11, s11, s29
	s_mul_i32 s28, s11, 0x88000
	s_add_u32 s28, s28, 0x9900000
	s_add_u32 s60, s24, s28
	s_addc_u32 s61, s25, 0
	s_mul_i32 s28, s11, 0x88000
	s_add_u32 s28, s28, 0xa180000
	s_add_u32 s62, s24, s28
	s_addc_u32 s63, s25, 0
	s_lshl_b32 s28, s55, 1
	s_add_u32 s28, s28, 8
	s_mul_i32 s28, s28, 0x220000
	v_add_u32_e32 v252, s28, v252
	s_lshl_b32 s28, s57, 5
	s_add_u32 s28, s28, s56
	v_add_u32_e32 v251, s28, v253
	s_movk_i32 s29, 128
	v_mul_lo_u32 v251, v251, s29
	v_lshl_add_u32 v251, v140, 4, v251
	s_movk_i32 s29, 144
	v_mul_lo_u32 v238, v253, s29
	v_lshl_add_u32 v238, v140, 4, v238
	s_movk_i32 s29, 136
	v_mul_lo_u32 v239, v253, s29
	v_lshl_add_u32 v239, v140, 3, v239
	v_add_u32_e32 v240, 0x1100, v239
	v_mov_b32_e32 v225, v143
	v_lshrrev_b32_e32 v226, 3, v225
	v_and_b32_e32 v227, 7, v225
	s_movk_i32 s29, 128
	v_mul_lo_u32 v246, v226, s29
	v_lshl_add_u32 v246, v227, 4, v246
	s_movk_i32 s29, 144
	v_mul_lo_u32 v241, v226, s29
	v_lshl_add_u32 v241, v227, 4, v241
	v_add_u32_e32 v225, 256, v143
	v_lshrrev_b32_e32 v226, 3, v225
	v_and_b32_e32 v227, 7, v225
	s_movk_i32 s29, 128
	v_mul_lo_u32 v247, v226, s29
	v_lshl_add_u32 v247, v227, 4, v247
	s_movk_i32 s29, 144
	v_mul_lo_u32 v242, v226, s29
	v_lshl_add_u32 v242, v227, 4, v242
	v_lshrrev_b32_e32 v226, 3, v143
	v_and_b32_e32 v227, 7, v143
	s_movk_i32 s29, 8704
	v_mul_lo_u32 v249, v226, s29
	v_lshl_add_u32 v249, v227, 4, v249
	v_add_u32_e32 v250, 0x44000, v249
	s_movk_i32 s29, 136
	v_mul_lo_u32 v244, v226, s29
	v_lshl_add_u32 v244, v227, 4, v244
	v_add_u32_e32 v245, 0x1100, v244
	s_barrier
	global_load_dwordx4 v[112:115], v251, s[58:59] offset:0
	global_load_dwordx4 v[116:119], v251, s[58:59] offset:32
	global_load_dwordx4 v[120:123], v251, s[58:59] offset:64
	global_load_dwordx4 v[124:127], v251, s[58:59] offset:96
	s_mov_b32 s1, 0
	s_min_u32 s0, s1, 67
	s_mul_i32 s0, s0, 0x2000
	s_add_u32 s64, s60, s0
	s_addc_u32 s65, s61, 0
	s_min_u32 s0, s1, 67
	s_lshl_b32 s0, s0, 7
	s_add_u32 s66, s62, s0
	s_addc_u32 s67, s63, 0
	global_load_dwordx4 v[176:179], v246, s[64:65]
	global_load_dwordx4 v[180:183], v247, s[64:65]
	global_load_dwordx4 v[212:215], v249, s[66:67]
	global_load_dwordx4 v[216:219], v250, s[66:67]
	s_waitcnt vmcnt(0)
	ds_write_b128 v241, v[176:179] offset:0
	ds_write_b128 v242, v[180:183] offset:0
	ds_write_b64 v244, v[212:213] offset:18432
	ds_write_b64 v244, v[214:215] offset:18440
	ds_write_b64 v245, v[216:217] offset:18432
	ds_write_b64 v245, v[218:219] offset:18440
	s_mov_b32 s1, 1
	s_min_u32 s0, s1, 67
	s_mul_i32 s0, s0, 0x2000
	s_add_u32 s64, s60, s0
	s_addc_u32 s65, s61, 0
	s_min_u32 s0, s1, 67
	s_lshl_b32 s0, s0, 7
	s_add_u32 s66, s62, s0
	s_addc_u32 s67, s63, 0
	global_load_dwordx4 v[176:179], v246, s[64:65]
	global_load_dwordx4 v[180:183], v247, s[64:65]
	s_waitcnt vmcnt(0)
	ds_write_b128 v241, v[176:179] offset:9216
	ds_write_b128 v242, v[180:183] offset:9216
	s_mov_b32 s1, 2
	s_mov_b32 s10, 1
	s_min_u32 s0, s1, 67
	s_mul_i32 s0, s0, 0x2000
	s_add_u32 s64, s60, s0
	s_addc_u32 s65, s61, 0
	s_min_u32 s0, s10, 67
	s_lshl_b32 s0, s0, 7
	s_add_u32 s66, s62, s0
	s_addc_u32 s67, s63, 0
	global_load_dwordx4 v[176:179], v246, s[64:65]
	global_load_dwordx4 v[180:183], v247, s[64:65]
	global_load_dwordx4 v[212:215], v249, s[66:67]
	global_load_dwordx4 v[216:219], v250, s[66:67]
	v_mov_b32_e32 v0, 0
	v_mov_b32_e32 v1, 0
	v_mov_b32_e32 v2, 0
	v_mov_b32_e32 v3, 0
	v_mov_b32_e32 v4, 0
	v_mov_b32_e32 v5, 0
	v_mov_b32_e32 v6, 0
	v_mov_b32_e32 v7, 0
	v_mov_b32_e32 v8, 0
	v_mov_b32_e32 v9, 0
	v_mov_b32_e32 v10, 0
	v_mov_b32_e32 v11, 0
	v_mov_b32_e32 v12, 0
	v_mov_b32_e32 v13, 0
	v_mov_b32_e32 v14, 0
	v_mov_b32_e32 v15, 0
	v_mov_b32_e32 v16, 0
	v_mov_b32_e32 v17, 0
	v_mov_b32_e32 v18, 0
	v_mov_b32_e32 v19, 0
	v_mov_b32_e32 v20, 0
	v_mov_b32_e32 v21, 0
	v_mov_b32_e32 v22, 0
	v_mov_b32_e32 v23, 0
	v_mov_b32_e32 v24, 0
	v_mov_b32_e32 v25, 0
	v_mov_b32_e32 v26, 0
	v_mov_b32_e32 v27, 0
	v_mov_b32_e32 v28, 0
	v_mov_b32_e32 v29, 0
	v_mov_b32_e32 v30, 0
	v_mov_b32_e32 v31, 0
	v_mov_b32_e32 v221, 0
	s_waitcnt lgkmcnt(0)
	s_barrier
	ds_read_b128 v[144:147], v238 offset:0
	ds_read_b128 v[148:151], v238 offset:4608
	ds_read_b128 v[152:155], v238 offset:32
	ds_read_b128 v[156:159], v238 offset:4640
	s_waitcnt lgkmcnt(3)
	v_mfma_f32_32x32x16_bf16 v[32:47], v[144:147], v[112:115], 0
	ds_read_b128 v[144:147], v238 offset:64
	s_waitcnt lgkmcnt(3)
	v_mfma_f32_32x32x16_bf16 v[48:63], v[148:151], v[112:115], 0
	ds_read_b128 v[148:151], v238 offset:4672
	s_waitcnt lgkmcnt(3)
	v_mfma_f32_32x32x16_bf16 v[32:47], v[152:155], v[116:119], v[32:47]
	ds_read_b128 v[152:155], v238 offset:96
	s_waitcnt lgkmcnt(3)
	v_mfma_f32_32x32x16_bf16 v[48:63], v[156:159], v[116:119], v[48:63]
	ds_read_b128 v[156:159], v238 offset:4704
	s_waitcnt lgkmcnt(3)
	v_mfma_f32_32x32x16_bf16 v[32:47], v[144:147], v[120:123], v[32:47]
	s_waitcnt lgkmcnt(2)
	v_mfma_f32_32x32x16_bf16 v[48:63], v[148:151], v[120:123], v[48:63]
	s_waitcnt lgkmcnt(1)
	v_mfma_f32_32x32x16_bf16 v[32:47], v[152:155], v[124:127], v[32:47]
	s_waitcnt lgkmcnt(0)
	v_mfma_f32_32x32x16_bf16 v[48:63], v[156:159], v[124:127], v[48:63]
	s_waitcnt lgkmcnt(0)
	s_barrier
	s_nop 7
	s_nop 3
	v_max3_f32 v223, v32, v33, v34
	v_max3_f32 v224, v40, v41, v42
	v_max3_f32 v225, v48, v49, v50
	v_max3_f32 v226, v56, v57, v58
	v_max3_f32 v223, v223, v35, v36
	v_max3_f32 v224, v224, v43, v44
	v_max3_f32 v225, v225, v51, v52
	v_max3_f32 v226, v226, v59, v60
	v_max3_f32 v223, v223, v37, v38
	v_max3_f32 v224, v224, v45, v46
	v_max3_f32 v225, v225, v53, v54
	v_max3_f32 v226, v226, v61, v62
	v_max_f32_e32 v223, v223, v39
	v_max_f32_e32 v224, v224, v47
	v_max_f32_e32 v225, v225, v55
	v_max_f32_e32 v226, v226, v63
	v_max3_f32 v222, v223, v224, v225
	v_max_f32_e32 v222, v222, v226
	v_mov_b32_e32 v227, v222
	s_nop 1
	v_permlane32_swap_b32_e32 v222, v227
	v_max_f32_e32 v222, v222, v227
	v_sub_f32_e32 v32, v32, v222
	v_sub_f32_e32 v33, v33, v222
	v_sub_f32_e32 v34, v34, v222
	v_sub_f32_e32 v35, v35, v222
	v_sub_f32_e32 v36, v36, v222
	v_sub_f32_e32 v37, v37, v222
	v_sub_f32_e32 v38, v38, v222
	v_sub_f32_e32 v39, v39, v222
	v_sub_f32_e32 v40, v40, v222
	v_sub_f32_e32 v41, v41, v222
	v_sub_f32_e32 v42, v42, v222
	v_sub_f32_e32 v43, v43, v222
	v_sub_f32_e32 v44, v44, v222
	v_sub_f32_e32 v45, v45, v222
	v_sub_f32_e32 v46, v46, v222
	v_sub_f32_e32 v47, v47, v222
	v_sub_f32_e32 v48, v48, v222
	v_sub_f32_e32 v49, v49, v222
	v_sub_f32_e32 v50, v50, v222
	v_sub_f32_e32 v51, v51, v222
	v_sub_f32_e32 v52, v52, v222
	v_sub_f32_e32 v53, v53, v222
	v_sub_f32_e32 v54, v54, v222
	v_sub_f32_e32 v55, v55, v222
	v_sub_f32_e32 v56, v56, v222
	v_sub_f32_e32 v57, v57, v222
	v_sub_f32_e32 v58, v58, v222
	v_sub_f32_e32 v59, v59, v222
	v_sub_f32_e32 v60, v60, v222
	v_sub_f32_e32 v61, v61, v222
	v_sub_f32_e32 v62, v62, v222
	v_sub_f32_e32 v63, v63, v222
	v_sub_f32_e32 v160, 0, v222
	v_sub_f32_e32 v161, 0, v222
	v_sub_f32_e32 v162, 0, v222
	v_sub_f32_e32 v163, 0, v222
	v_sub_f32_e32 v164, 0, v222
	v_sub_f32_e32 v165, 0, v222
	v_sub_f32_e32 v166, 0, v222
	v_sub_f32_e32 v167, 0, v222
	v_sub_f32_e32 v168, 0, v222
	v_sub_f32_e32 v169, 0, v222
	v_sub_f32_e32 v170, 0, v222
	v_sub_f32_e32 v171, 0, v222
	v_sub_f32_e32 v172, 0, v222
	v_sub_f32_e32 v173, 0, v222
	v_sub_f32_e32 v174, 0, v222
	v_sub_f32_e32 v175, 0, v222
	s_mov_b32 s69, 0
	s_mov_b32 s68, 0

; DI unsigned pack2(float lo, float hi) { f32x2_t v = {lo, hi}; bf16x2_t r = __builtin_convertvector(v, bf16x2_t); return __builtin_bit_cast(unsigned, r); }
; DI float xhalf_sum(float x) { auto r = __builtin_amdgcn_permlane32_swap(__float_as_uint(x), __float_as_uint(x), false, false); return __uint_as_float(r[0]) + __uint_as_float(r[1]); }
; template <int DQK>
; DI void attn_item(const bf16_t* __restrict__ Q, const bf16_t* __restrict__ Kp, const bf16_t* __restrict__ Vt, int q0, int nkeys,
;                   bf16_t* __restrict__ mix, int colbase, int b, char* smem) {
;     ...
;   const int nt = nkeys >> 6;
;   A_LOAD(p, 0)
;   A_LOAD(q, 64)
;   A_WRITE(p, 0)
;   __syncthreads();
;   if (nt > 2) A_LOAD(p, 128)
;   for (int kt = 0; kt < nt; kt += 2) {
;     A_TILE(0)
;     A_WRITE(q, 1)
;     __syncthreads();
;     if (kt + 3 < nt) A_LOAD(q, (kt + 3) << 6)
;     A_TILE(1)
;     if (kt + 2 < nt) A_WRITE(p, 0)
;     __syncthreads();
;     if (kt + 4 < nt) A_LOAD(p, (kt + 4) << 6)
;   }
;     ...
;   l = xhalf_sum(l);
;   const float inv = 1.0f / l;
;   const int kp = q0 + wave * 32 + r;
;   bf16_t* orow = mix + (size_t)row_of(b, kp) * D + colbase;
; #pragma unroll
;   for (int g = 0; g < 4; ++g) {
;     uint2 w0, w1;
;     w0.x = pack2(o0[4 * g] * inv, o0[4 * g + 1] * inv); w0.y = pack2(o0[4 * g + 2] * inv, o0[4 * g + 3] * inv);
;     w1.x = pack2(o1[4 * g] * inv, o1[4 * g + 1] * inv); w1.y = pack2(o1[4 * g + 2] * inv, o1[4 * g + 3] * inv);
;     *(uint2*)(orow + 8 * g + 4 * h) = w0;
;     *(uint2*)(orow + 32 + 8 * g + 4 * h) = w1;
;   }
.Lat_nors_9:
	s_waitcnt lgkmcnt(3)
	v_mfma_f32_32x32x16_bf16 v[48:63], v[148:151], v[120:123], v[48:63]
	ds_read_b128 v[148:151], v238 offset:6784
	v_exp_f32_e32 v64, v64
	v_exp_f32_e32 v65, v65
	v_exp_f32_e32 v66, v66
	v_exp_f32_e32 v67, v67
	s_waitcnt lgkmcnt(3)
	v_mfma_f32_32x32x16_bf16 v[32:47], v[152:155], v[124:127], v[32:47]
	ds_read_b128 v[152:155], v238 offset:160
	v_exp_f32_e32 v68, v68
	v_exp_f32_e32 v69, v69
	v_exp_f32_e32 v70, v70
	v_exp_f32_e32 v71, v71
	s_waitcnt lgkmcnt(3)
	v_mfma_f32_32x32x16_bf16 v[48:63], v[156:159], v[124:127], v[48:63]
	ds_read_b128 v[156:159], v238 offset:6816
	v_exp_f32_e32 v72, v72
	v_exp_f32_e32 v73, v73
	v_exp_f32_e32 v74, v74
	v_exp_f32_e32 v75, v75
	s_waitcnt lgkmcnt(3)
	v_mfma_f32_32x32x16_bf16 v[32:47], v[144:147], v[128:131], v[32:47]
	v_exp_f32_e32 v76, v76
	v_exp_f32_e32 v77, v77
	v_exp_f32_e32 v78, v78
	v_exp_f32_e32 v79, v79
	s_waitcnt lgkmcnt(2)
	v_mfma_f32_32x32x16_bf16 v[48:63], v[148:151], v[128:131], v[48:63]
	v_exp_f32_e32 v80, v80
	v_exp_f32_e32 v81, v81
	v_exp_f32_e32 v82, v82
	v_exp_f32_e32 v83, v83
	s_waitcnt lgkmcnt(1)
	v_mfma_f32_32x32x16_bf16 v[32:47], v[152:155], v[132:135], v[32:47]
	v_exp_f32_e32 v84, v84
	v_exp_f32_e32 v85, v85
	v_exp_f32_e32 v86, v86
	v_exp_f32_e32 v87, v87
	s_waitcnt lgkmcnt(0)
	v_mfma_f32_32x32x16_bf16 v[48:63], v[156:159], v[132:135], v[48:63]
	v_exp_f32_e32 v88, v88
	v_exp_f32_e32 v89, v89
	v_exp_f32_e32 v90, v90
	v_exp_f32_e32 v91, v91
	v_exp_f32_e32 v92, v92
	v_exp_f32_e32 v93, v93
	v_exp_f32_e32 v94, v94
	v_exp_f32_e32 v95, v95
	v_add_u32_e32 v223, 0x8a00, v239
	v_add_u32_e32 v224, 0x8a00, v240
	ds_read2_b64 v[144:147], v223 offset0:0 offset1:2
	ds_read2_b64 v[148:151], v224 offset0:0 offset1:2
	ds_read2_b64 v[152:155], v223 offset0:4 offset1:6
	ds_read2_b64 v[156:159], v224 offset0:4 offset1:6
	v_cvt_pk_bf16_f32 v96, v64, v65
	v_cvt_pk_bf16_f32 v97, v66, v67
	v_cvt_pk_bf16_f32 v98, v68, v69
	v_cvt_pk_bf16_f32 v99, v70, v71
	v_add_f32_e32 v231, v64, v68
	v_add_f32_e32 v232, v65, v69
	v_add_f32_e32 v233, v66, v70
	v_add_f32_e32 v237, v67, v71
	s_waitcnt lgkmcnt(3)
	v_mfma_f32_32x32x16_bf16 v[0:15], v[144:147], v[96:99], v[0:15]
	ds_read2_b64 v[144:147], v223 offset0:8 offset1:10
	s_waitcnt lgkmcnt(3)
	v_mfma_f32_32x32x16_bf16 v[16:31], v[148:151], v[96:99], v[16:31]
	ds_read2_b64 v[148:151], v224 offset0:8 offset1:10
	v_cvt_pk_bf16_f32 v100, v72, v73
	v_cvt_pk_bf16_f32 v101, v74, v75
	v_cvt_pk_bf16_f32 v102, v76, v77
	v_cvt_pk_bf16_f32 v103, v78, v79
	v_add_f32_e32 v231, v231, v72
	v_add_f32_e32 v232, v232, v73
	v_add_f32_e32 v233, v233, v74
	v_add_f32_e32 v237, v237, v75
	v_add_f32_e32 v231, v231, v76
	v_add_f32_e32 v232, v232, v77
	v_add_f32_e32 v233, v233, v78
	v_add_f32_e32 v237, v237, v79
	s_waitcnt lgkmcnt(3)
	v_mfma_f32_32x32x16_bf16 v[0:15], v[152:155], v[100:103], v[0:15]
	ds_read2_b64 v[152:155], v223 offset0:12 offset1:14
	s_waitcnt lgkmcnt(3)
	v_mfma_f32_32x32x16_bf16 v[16:31], v[156:159], v[100:103], v[16:31]
	ds_read2_b64 v[156:159], v224 offset0:12 offset1:14
	v_cvt_pk_bf16_f32 v104, v80, v81
	v_cvt_pk_bf16_f32 v105, v82, v83
	v_cvt_pk_bf16_f32 v106, v84, v85
	v_cvt_pk_bf16_f32 v107, v86, v87
	v_add_f32_e32 v231, v231, v80
	v_add_f32_e32 v232, v232, v81
	v_add_f32_e32 v233, v233, v82
	v_add_f32_e32 v237, v237, v83
	v_add_f32_e32 v231, v231, v84
	v_add_f32_e32 v232, v232, v85
	v_add_f32_e32 v233, v233, v86
	v_add_f32_e32 v237, v237, v87
	s_waitcnt lgkmcnt(3)
	v_mfma_f32_32x32x16_bf16 v[0:15], v[144:147], v[104:107], v[0:15]
	s_waitcnt lgkmcnt(2)
	v_mfma_f32_32x32x16_bf16 v[16:31], v[148:151], v[104:107], v[16:31]
	v_cvt_pk_bf16_f32 v108, v88, v89
	v_cvt_pk_bf16_f32 v109, v90, v91
	v_cvt_pk_bf16_f32 v110, v92, v93
	v_cvt_pk_bf16_f32 v111, v94, v95
	v_add_f32_e32 v231, v231, v88
	v_add_f32_e32 v232, v232, v89
	v_add_f32_e32 v233, v233, v90
	v_add_f32_e32 v237, v237, v91
	v_add_f32_e32 v231, v231, v92
	v_add_f32_e32 v232, v232, v93
	v_add_f32_e32 v233, v233, v94
	v_add_f32_e32 v237, v237, v95
	s_waitcnt lgkmcnt(1)
	v_mfma_f32_32x32x16_bf16 v[0:15], v[152:155], v[108:111], v[0:15]
	s_waitcnt lgkmcnt(0)
	v_mfma_f32_32x32x16_bf16 v[16:31], v[156:159], v[108:111], v[16:31]
	v_add_f32_e32 v231, v231, v232
	v_add_f32_e32 v233, v233, v237
	v_add_f32_e32 v231, v231, v233
	v_add_f32_e32 v221, v221, v231
	s_add_u32 s68, s68, 1
	s_waitcnt lgkmcnt(0)
	s_barrier
	s_cmp_lt_u32 s68, 68
	s_cbranch_scc1 .Lat_loop_m
	s_nop 7
	v_mov_b32_e32 v223, v221
	s_nop 1
	v_permlane32_swap_b32_e32 v221, v223
	v_add_f32_e32 v221, v221, v223
	v_rcp_f32_e32 v224, v221
	v_add_u32_e32 v226, 0x220000, v252
	s_nop 0
	v_mul_f32_e32 v96, v0, v224
	v_mul_f32_e32 v97, v1, v224
	v_mul_f32_e32 v98, v2, v224
	v_mul_f32_e32 v99, v3, v224
	v_cvt_pk_bf16_f32 v144, v96, v97
	v_cvt_pk_bf16_f32 v145, v98, v99
	global_store_dwordx2 v252, v[144:145], s[72:73] offset:0
	v_mul_f32_e32 v96, v16, v224
	v_mul_f32_e32 v97, v17, v224
	v_mul_f32_e32 v98, v18, v224
	v_mul_f32_e32 v99, v19, v224
	v_cvt_pk_bf16_f32 v146, v96, v97
	v_cvt_pk_bf16_f32 v147, v98, v99
	global_store_dwordx2 v226, v[146:147], s[72:73] offset:0
	v_mul_f32_e32 v96, v4, v224
	v_mul_f32_e32 v97, v5, v224
	v_mul_f32_e32 v98, v6, v224
	v_mul_f32_e32 v99, v7, v224
	v_cvt_pk_bf16_f32 v148, v96, v97
	v_cvt_pk_bf16_f32 v149, v98, v99
	global_store_dwordx2 v252, v[148:149], s[72:73] offset:16
	v_mul_f32_e32 v96, v20, v224
	v_mul_f32_e32 v97, v21, v224
	v_mul_f32_e32 v98, v22, v224
	v_mul_f32_e32 v99, v23, v224
	v_cvt_pk_bf16_f32 v150, v96, v97
	v_cvt_pk_bf16_f32 v151, v98, v99
	global_store_dwordx2 v226, v[150:151], s[72:73] offset:16
	v_mul_f32_e32 v96, v8, v224
	v_mul_f32_e32 v97, v9, v224
	v_mul_f32_e32 v98, v10, v224
	v_mul_f32_e32 v99, v11, v224
	v_cvt_pk_bf16_f32 v152, v96, v97
	v_cvt_pk_bf16_f32 v153, v98, v99
	global_store_dwordx2 v252, v[152:153], s[72:73] offset:32
	v_mul_f32_e32 v96, v24, v224
	v_mul_f32_e32 v97, v25, v224
	v_mul_f32_e32 v98, v26, v224
	v_mul_f32_e32 v99, v27, v224
	v_cvt_pk_bf16_f32 v154, v96, v97
	v_cvt_pk_bf16_f32 v155, v98, v99
	global_store_dwordx2 v226, v[154:155], s[72:73] offset:32
	v_mul_f32_e32 v96, v12, v224
	v_mul_f32_e32 v97, v13, v224
	v_mul_f32_e32 v98, v14, v224
	v_mul_f32_e32 v99, v15, v224
	v_cvt_pk_bf16_f32 v156, v96, v97
	v_cvt_pk_bf16_f32 v157, v98, v99
	global_store_dwordx2 v252, v[156:157], s[72:73] offset:48
	v_mul_f32_e32 v96, v28, v224
	v_mul_f32_e32 v97, v29, v224
	v_mul_f32_e32 v98, v30, v224
	v_mul_f32_e32 v99, v31, v224
	v_cvt_pk_bf16_f32 v158, v96, v97
	v_cvt_pk_bf16_f32 v159, v98, v99
	global_store_dwordx2 v226, v[158:159], s[72:73] offset:48
	s_branch .Lat2_fb_ret
; DI void phase_attn(const Params& p, int layer, char* smem) {
;   const int n_lat = 96 * 32, n_ctx = (layer == 0) ? 96 * 2 : 0;
;   for (int it = blockIdx.x; it < n_lat + n_ctx; it += gridDim.x) {
;     int combo, qb;
;     if (it < n_lat) { int xc = it & 7, j = it >> 3; combo = (j >> 5) * 8 + xc; qb = 2 + (j & 31); }
;     else { int r = it - n_lat; combo = r >> 1; qb = r & 1; }
;     const int type = combo / 48, bh = combo % 48;
;     attn_dispatch(p, type, bh / 6, bh % 6, qb, smem);
;   }
;   ytrans_loop(p, smem);
.Lat2_fb_ret:
	s_add_u32 s56, s56, 128
	s_add_u32 s75, s75, 1
	s_cmp_lt_u32 s75, 2
	s_cbranch_scc1 .Lat2_fb_loop
	s_branch .Lat2_next
.Lat2_done:
	s_waitcnt vmcnt(0)
	s_barrier
	v_lshlrev_b32_e32 v248, 2, v143
	v_add_u32_e32 v248, 0xac00, v248
	ds_read_b32 v136, v248 offset:0
	ds_read_b32 v137, v248 offset:1024
	ds_read_b32 v138, v248 offset:2048
	ds_read_b32 v139, v248 offset:3072
	ds_read_b32 v141, v248 offset:4096
	ds_read_b32 v142, v248 offset:5120
	ds_read_b32 v188, v248 offset:6144
	ds_read_b32 v189, v248 offset:7168
	ds_read_b32 v190, v248 offset:8192
	ds_read_b32 v191, v248 offset:9216
	ds_read_b32 v192, v248 offset:10240
	ds_read_b32 v193, v248 offset:11264
	ds_read_b32 v194, v248 offset:12288
	ds_read_b32 v195, v248 offset:13312
	ds_read_b32 v196, v248 offset:14336
	ds_read_b32 v197, v248 offset:15360
	ds_read_b32 v198, v248 offset:16384
	ds_read_b32 v199, v248 offset:17408
	ds_read_b32 v200, v248 offset:18432
	ds_read_b32 v201, v248 offset:19456
	ds_read_b32 v202, v248 offset:20480
	ds_read_b32 v203, v248 offset:21504
	ds_read_b32 v204, v248 offset:22528
	ds_read_b32 v205, v248 offset:23552
	ds_read_b32 v206, v248 offset:24576
	ds_read_b32 v207, v248 offset:25600
	ds_read_b32 v208, v248 offset:26624
	ds_read_b32 v209, v248 offset:27648
	ds_read_b32 v210, v248 offset:28672
	ds_read_b32 v211, v248 offset:29696
	ds_read_b32 v212, v248 offset:30720
	ds_read_b32 v234, v248 offset:31744
	ds_read_b32 v235, v248 offset:32768
	ds_read_b32 v236, v248 offset:33792
	s_add_u32 s0, s52, 0x600
	v_readlane_b32 s52, v254, 0
	v_readlane_b32 s53, v254, 1
	v_readlane_b32 s54, v254, 2
	v_readlane_b32 s55, v254, 3
	v_readlane_b32 s56, v254, 4
	v_readlane_b32 s57, v254, 5
	v_readlane_b32 s58, v254, 6
	v_readlane_b32 s59, v254, 7
	v_readlane_b32 s60, v254, 8
	v_readlane_b32 s61, v254, 9
	v_readlane_b32 s62, v254, 10
	v_readlane_b32 s63, v254, 11
	v_readlane_b32 s64, v254, 12
	v_readlane_b32 s65, v254, 13
	v_readlane_b32 s66, v254, 14
	v_readlane_b32 s67, v254, 15
	v_readlane_b32 s68, v254, 16
	v_readlane_b32 s69, v254, 17
	v_readlane_b32 s70, v254, 18
	v_readlane_b32 s71, v254, 19
	v_readlane_b32 s72, v254, 20
	v_readlane_b32 s73, v254, 21
	v_readlane_b32 s74, v254, 22
	v_readlane_b32 s75, v254, 23
	v_readlane_b32 s76, v254, 24
	v_readlane_b32 s77, v254, 25
	v_readlane_b32 s78, v254, 26
	v_readlane_b32 s79, v254, 27
	v_readlane_b32 s80, v254, 28
	v_readlane_b32 s81, v254, 29
	v_readlane_b32 s82, v254, 30
	v_readlane_b32 s83, v254, 31
	v_readlane_b32 s84, v254, 32
	v_readlane_b32 s85, v254, 33
	v_readlane_b32 s86, v254, 34
	v_readlane_b32 s87, v254, 35
	v_readlane_b32 s88, v254, 36
	v_readlane_b32 s89, v254, 37
	v_readlane_b32 s90, v254, 38
	v_readlane_b32 s91, v254, 39
	s_waitcnt lgkmcnt(0)
	s_mov_b32 s13, s0
	s_cmp_ge_i32 s13, s12
	s_cbranch_scc0 .LBB0_1453
	s_branch .LBB0_1446
